# GEMM epilogue stores of P1 / P16 (shared code) and P4 carry the nt cache hint (streaming outputs should not displace the operand tiles in L2)
# baseline (speedup 1.0000x reference)
; __device__ __forceinline__ unsigned cvt_pk_bf16(float lo, float hi) { const f32x2 v = {lo, hi}; return __builtin_bit_cast(unsigned, __builtin_convertvector(v, bf16x2_t)); }
; __device__ __forceinline__ float silu(float x) { return x * sigm(x); }
;     __device__ __forceinline__ void operator()(AccRef acc, const Unit& u, int wr, int wc, int fr, int fq) const {
;         const int col0 = u.pn * 128 + wc * 32 + 8 * fq;
; #pragma unroll
;         for (int ai = 0; ai < 2; ++ai)
; #pragma unroll
;             for (int m = 0; m < 4; ++m) {
;                 const f32x4 g0 = acc[ai][0][m][0], g1 = acc[ai][0][m][1], u0 = acc[ai][1][m][0], u1 = acc[ai][1][m][1];
;                 u32x4 w;
;                 w.x = cvt_pk_bf16(silu(g0[0]) * u0[0], silu(g0[1]) * u0[1]); w.y = cvt_pk_bf16(silu(g0[2]) * u0[2], silu(g0[3]) * u0[3]);
;                 w.z = cvt_pk_bf16(silu(g1[0]) * u1[0], silu(g1[1]) * u1[1]); w.w = cvt_pk_bf16(silu(g1[2]) * u1[2], silu(g1[3]) * u1[3]);
;                 if (EPI_ROWS(ai, m) < MT) *(u32x4*)(O + (size_t)EPI_ROWS(ai, m) * FF + col0) = w;
;             }
.LBB0_166:
	v_lshl_or_b32 v140, s26, 7, v144
	v_lshl_add_u32 v148, s28, 8, v142
	v_ashrrev_i32_e32 v141, 31, v140
	v_cmp_gt_i32_e32 vcc, s62, v148
	s_and_saveexec_b64 s[26:27], vcc
	s_cbranch_execz .LBB0_168
	v_mul_f32_e32 v149, 0xbfb8aa3b, v126
	v_exp_f32_e32 v150, v149
	v_mul_f32_e32 v149, 0xbfb8aa3b, v127
	v_exp_f32_e32 v151, v149
	s_nop 0
	v_pk_add_f32 v[150:151], v[150:151], 1.0 op_sel_hi:[1,0]
	s_nop 0
	v_rcp_f32_e32 v151, v151
	v_mul_f32_e32 v152, 0xbfb8aa3b, v124
	v_mul_f32_e32 v153, 0xbfb8aa3b, v125
	v_exp_f32_e32 v152, v152
	v_exp_f32_e32 v153, v153
	v_rcp_f32_e32 v150, v150
	s_nop 0
	v_pk_mul_f32 v[126:127], v[126:127], v[150:151]
	v_pk_add_f32 v[152:153], v[152:153], 1.0 op_sel_hi:[1,0]
	v_pk_mul_f32 v[122:123], v[126:127], v[122:123]
	v_cvt_pk_bf16_f32 v123, v122, v123
	v_rcp_f32_e32 v127, v153
	v_mul_f32_e32 v149, 0xbfb8aa3b, v118
	v_exp_f32_e32 v150, v149
	v_mul_f32_e32 v149, 0xbfb8aa3b, v119
	v_exp_f32_e32 v151, v149
	v_rcp_f32_e32 v126, v152
	s_nop 0
	v_pk_mul_f32 v[124:125], v[124:125], v[126:127]
	v_pk_add_f32 v[150:151], v[150:151], 1.0 op_sel_hi:[1,0]
	v_pk_mul_f32 v[120:121], v[124:125], v[120:121]
	v_cvt_pk_bf16_f32 v122, v120, v121
	v_rcp_f32_e32 v121, v151
	v_mul_f32_e32 v124, 0xbfb8aa3b, v116
	v_mul_f32_e32 v125, 0xbfb8aa3b, v117
	v_exp_f32_e32 v124, v124
	v_exp_f32_e32 v125, v125
	v_rcp_f32_e32 v120, v150
	s_nop 0
	v_pk_mul_f32 v[118:119], v[118:119], v[120:121]
	v_pk_add_f32 v[124:125], v[124:125], 1.0 op_sel_hi:[1,0]
	v_pk_mul_f32 v[114:115], v[118:119], v[114:115]
	v_cvt_pk_bf16_f32 v121, v114, v115
	v_rcp_f32_e32 v115, v125
	v_rcp_f32_e32 v114, v124
	s_nop 0
	v_pk_mul_f32 v[114:115], v[116:117], v[114:115]
	s_nop 0
	v_pk_mul_f32 v[112:113], v[114:115], v[112:113]
	s_nop 0
	v_cvt_pk_bf16_f32 v120, v112, v113
	v_mov_b64_e32 v[112:113], s[2:3]
	v_mad_i64_i32 v[112:113], s[40:41], v148, s63, v[112:113]
	v_lshl_add_u64 v[112:113], v[140:141], 1, v[112:113]
	global_store_dwordx4 v[112:113], v[120:123], off nt
.LBB0_168:
	s_or_b64 exec, exec, s[26:27]
	v_or_b32_e32 v112, 16, v148
	v_cmp_gt_i32_e32 vcc, s62, v112
	s_and_saveexec_b64 s[26:27], vcc
	s_cbranch_execz .LBB0_170
	v_mul_f32_e32 v113, 0xbfb8aa3b, v110
	v_exp_f32_e32 v114, v113
	v_mul_f32_e32 v113, 0xbfb8aa3b, v111
	v_exp_f32_e32 v115, v113
	s_nop 0
	v_pk_add_f32 v[114:115], v[114:115], 1.0 op_sel_hi:[1,0]
	s_nop 0
	v_rcp_f32_e32 v115, v115
	v_mul_f32_e32 v116, 0xbfb8aa3b, v108
	v_mul_f32_e32 v117, 0xbfb8aa3b, v109
	v_exp_f32_e32 v116, v116
	v_exp_f32_e32 v117, v117
	v_rcp_f32_e32 v114, v114
	s_nop 0
	v_pk_mul_f32 v[110:111], v[110:111], v[114:115]
	v_pk_add_f32 v[116:117], v[116:117], 1.0 op_sel_hi:[1,0]
	v_pk_mul_f32 v[106:107], v[110:111], v[106:107]
	v_cvt_pk_bf16_f32 v107, v106, v107
	v_rcp_f32_e32 v111, v117
	v_mul_f32_e32 v113, 0xbfb8aa3b, v102
	v_exp_f32_e32 v114, v113
	v_mul_f32_e32 v113, 0xbfb8aa3b, v103
	v_exp_f32_e32 v115, v113
	v_rcp_f32_e32 v110, v116
	s_nop 0
	v_pk_mul_f32 v[108:109], v[108:109], v[110:111]
	v_pk_add_f32 v[114:115], v[114:115], 1.0 op_sel_hi:[1,0]
	v_pk_mul_f32 v[104:105], v[108:109], v[104:105]
	v_cvt_pk_bf16_f32 v106, v104, v105
	v_rcp_f32_e32 v105, v115
	v_mul_f32_e32 v108, 0xbfb8aa3b, v100
	v_mul_f32_e32 v109, 0xbfb8aa3b, v101
	v_exp_f32_e32 v108, v108
	v_exp_f32_e32 v109, v109
	v_rcp_f32_e32 v104, v114
	s_nop 0
	v_pk_mul_f32 v[102:103], v[102:103], v[104:105]
	v_pk_add_f32 v[108:109], v[108:109], 1.0 op_sel_hi:[1,0]
	v_pk_mul_f32 v[98:99], v[102:103], v[98:99]
	v_cvt_pk_bf16_f32 v105, v98, v99
	v_rcp_f32_e32 v99, v109
	v_rcp_f32_e32 v98, v108
	s_nop 0
	v_pk_mul_f32 v[98:99], v[100:101], v[98:99]
	s_nop 0
	v_pk_mul_f32 v[96:97], v[98:99], v[96:97]
	s_nop 0
	v_cvt_pk_bf16_f32 v104, v96, v97
	v_mov_b64_e32 v[96:97], s[2:3]
	v_mad_i64_i32 v[96:97], s[40:41], v112, s63, v[96:97]
	v_lshl_add_u64 v[96:97], v[140:141], 1, v[96:97]
	global_store_dwordx4 v[96:97], v[104:107], off nt
.LBB0_170:
	s_or_b64 exec, exec, s[26:27]
	v_or_b32_e32 v96, 32, v148
	v_cmp_gt_i32_e32 vcc, s62, v96
	s_and_saveexec_b64 s[26:27], vcc
	s_cbranch_execz .LBB0_172
	v_mul_f32_e32 v97, 0xbfb8aa3b, v94
	v_exp_f32_e32 v98, v97
	v_mul_f32_e32 v97, 0xbfb8aa3b, v95
	v_exp_f32_e32 v99, v97
	s_nop 0
	v_pk_add_f32 v[98:99], v[98:99], 1.0 op_sel_hi:[1,0]
	s_nop 0
	v_rcp_f32_e32 v99, v99
	v_mul_f32_e32 v100, 0xbfb8aa3b, v92
	v_mul_f32_e32 v101, 0xbfb8aa3b, v93
	v_exp_f32_e32 v100, v100
	v_exp_f32_e32 v101, v101
	v_rcp_f32_e32 v98, v98
	s_nop 0
	v_pk_mul_f32 v[94:95], v[94:95], v[98:99]
	v_pk_add_f32 v[100:101], v[100:101], 1.0 op_sel_hi:[1,0]
	v_pk_mul_f32 v[90:91], v[94:95], v[90:91]
	v_cvt_pk_bf16_f32 v91, v90, v91
	v_rcp_f32_e32 v95, v101
	v_mul_f32_e32 v97, 0xbfb8aa3b, v86
	v_exp_f32_e32 v98, v97
	v_mul_f32_e32 v97, 0xbfb8aa3b, v87
	v_exp_f32_e32 v99, v97
	v_rcp_f32_e32 v94, v100
	s_nop 0
	v_pk_mul_f32 v[92:93], v[92:93], v[94:95]
	v_pk_add_f32 v[98:99], v[98:99], 1.0 op_sel_hi:[1,0]
	v_pk_mul_f32 v[88:89], v[92:93], v[88:89]
	v_cvt_pk_bf16_f32 v90, v88, v89
	v_rcp_f32_e32 v89, v99
	v_mul_f32_e32 v92, 0xbfb8aa3b, v84
	v_mul_f32_e32 v93, 0xbfb8aa3b, v85
	v_exp_f32_e32 v92, v92
	v_exp_f32_e32 v93, v93
	v_rcp_f32_e32 v88, v98
	s_nop 0
	v_pk_mul_f32 v[86:87], v[86:87], v[88:89]
	v_pk_add_f32 v[92:93], v[92:93], 1.0 op_sel_hi:[1,0]
	v_pk_mul_f32 v[82:83], v[86:87], v[82:83]
	v_cvt_pk_bf16_f32 v89, v82, v83
	v_rcp_f32_e32 v83, v93
	v_rcp_f32_e32 v82, v92
	s_nop 0
	v_pk_mul_f32 v[82:83], v[84:85], v[82:83]
	s_nop 0
	v_pk_mul_f32 v[80:81], v[82:83], v[80:81]
	s_nop 0
	v_cvt_pk_bf16_f32 v88, v80, v81
	v_mov_b64_e32 v[80:81], s[2:3]
	v_mad_i64_i32 v[80:81], s[40:41], v96, s63, v[80:81]
	v_lshl_add_u64 v[80:81], v[140:141], 1, v[80:81]
	global_store_dwordx4 v[80:81], v[88:91], off nt
; __device__ __forceinline__ unsigned cvt_pk_bf16(float lo, float hi) { const f32x2 v = {lo, hi}; return __builtin_bit_cast(unsigned, __builtin_convertvector(v, bf16x2_t)); }
; __device__ __forceinline__ float silu(float x) { return x * sigm(x); }
;     __device__ __forceinline__ void operator()(AccRef acc, const Unit& u, int wr, int wc, int fr, int fq) const {
;     ...
;             for (int m = 0; m < 4; ++m) {
;                 const f32x4 g0 = acc[ai][0][m][0], g1 = acc[ai][0][m][1], u0 = acc[ai][1][m][0], u1 = acc[ai][1][m][1];
;                 u32x4 w;
;                 w.x = cvt_pk_bf16(silu(g0[0]) * u0[0], silu(g0[1]) * u0[1]); w.y = cvt_pk_bf16(silu(g0[2]) * u0[2], silu(g0[3]) * u0[3]);
;                 w.z = cvt_pk_bf16(silu(g1[0]) * u1[0], silu(g1[1]) * u1[1]); w.w = cvt_pk_bf16(silu(g1[2]) * u1[2], silu(g1[3]) * u1[3]);
;                 if (EPI_ROWS(ai, m) < MT) *(u32x4*)(O + (size_t)EPI_ROWS(ai, m) * FF + col0) = w;
.LBB0_172:
	s_or_b64 exec, exec, s[26:27]
	v_or_b32_e32 v80, 48, v148
	v_cmp_gt_i32_e32 vcc, s62, v80
	s_and_saveexec_b64 s[26:27], vcc
	s_cbranch_execz .LBB0_174
	v_mul_f32_e32 v81, 0xbfb8aa3b, v78
	v_exp_f32_e32 v82, v81
	v_mul_f32_e32 v81, 0xbfb8aa3b, v79
	v_exp_f32_e32 v83, v81
	s_nop 0
	v_pk_add_f32 v[82:83], v[82:83], 1.0 op_sel_hi:[1,0]
	s_nop 0
	v_rcp_f32_e32 v83, v83
	v_mul_f32_e32 v84, 0xbfb8aa3b, v76
	v_mul_f32_e32 v85, 0xbfb8aa3b, v77
	v_exp_f32_e32 v84, v84
	v_exp_f32_e32 v85, v85
	v_rcp_f32_e32 v82, v82
	s_nop 0
	v_pk_mul_f32 v[78:79], v[78:79], v[82:83]
	v_pk_add_f32 v[84:85], v[84:85], 1.0 op_sel_hi:[1,0]
	v_pk_mul_f32 v[74:75], v[78:79], v[74:75]
	v_cvt_pk_bf16_f32 v75, v74, v75
	v_rcp_f32_e32 v79, v85
	v_mul_f32_e32 v81, 0xbfb8aa3b, v70
	v_exp_f32_e32 v82, v81
	v_mul_f32_e32 v81, 0xbfb8aa3b, v71
	v_exp_f32_e32 v83, v81
	v_rcp_f32_e32 v78, v84
	s_nop 0
	v_pk_mul_f32 v[76:77], v[76:77], v[78:79]
	v_pk_add_f32 v[82:83], v[82:83], 1.0 op_sel_hi:[1,0]
	v_pk_mul_f32 v[72:73], v[76:77], v[72:73]
	v_cvt_pk_bf16_f32 v74, v72, v73
	v_rcp_f32_e32 v73, v83
	v_mul_f32_e32 v76, 0xbfb8aa3b, v68
	v_mul_f32_e32 v77, 0xbfb8aa3b, v69
	v_exp_f32_e32 v76, v76
	v_exp_f32_e32 v77, v77
	v_rcp_f32_e32 v72, v82
	s_nop 0
	v_pk_mul_f32 v[70:71], v[70:71], v[72:73]
	v_pk_add_f32 v[76:77], v[76:77], 1.0 op_sel_hi:[1,0]
	v_pk_mul_f32 v[66:67], v[70:71], v[66:67]
	v_cvt_pk_bf16_f32 v73, v66, v67
	v_rcp_f32_e32 v67, v77
	v_rcp_f32_e32 v66, v76
	s_nop 0
	v_pk_mul_f32 v[66:67], v[68:69], v[66:67]
	s_nop 0
	v_pk_mul_f32 v[64:65], v[66:67], v[64:65]
	s_nop 0
	v_cvt_pk_bf16_f32 v72, v64, v65
	v_mov_b64_e32 v[64:65], s[2:3]
	v_mad_i64_i32 v[64:65], s[40:41], v80, s63, v[64:65]
	v_lshl_add_u64 v[64:65], v[140:141], 1, v[64:65]
	global_store_dwordx4 v[64:65], v[72:75], off nt
.LBB0_174:
	s_or_b64 exec, exec, s[26:27]
	v_add_u32_e32 v64, 0x80, v148
	v_cmp_gt_i32_e32 vcc, s62, v64
	s_and_saveexec_b64 s[26:27], vcc
	s_cbranch_execz .LBB0_176
	v_mul_f32_e32 v65, 0xbfb8aa3b, v62
	v_exp_f32_e32 v66, v65
	v_mul_f32_e32 v65, 0xbfb8aa3b, v63
	v_exp_f32_e32 v67, v65
	s_nop 0
	v_pk_add_f32 v[66:67], v[66:67], 1.0 op_sel_hi:[1,0]
	s_nop 0
	v_rcp_f32_e32 v67, v67
	v_mul_f32_e32 v68, 0xbfb8aa3b, v60
	v_mul_f32_e32 v69, 0xbfb8aa3b, v61
	v_exp_f32_e32 v68, v68
	v_exp_f32_e32 v69, v69
	v_rcp_f32_e32 v66, v66
	s_nop 0
	v_pk_mul_f32 v[62:63], v[62:63], v[66:67]
	v_pk_add_f32 v[68:69], v[68:69], 1.0 op_sel_hi:[1,0]
	v_pk_mul_f32 v[58:59], v[62:63], v[58:59]
	v_cvt_pk_bf16_f32 v59, v58, v59
	v_rcp_f32_e32 v63, v69
	v_mul_f32_e32 v65, 0xbfb8aa3b, v54
	v_exp_f32_e32 v66, v65
	v_mul_f32_e32 v65, 0xbfb8aa3b, v55
	v_exp_f32_e32 v67, v65
	v_rcp_f32_e32 v62, v68
	s_nop 0
	v_pk_mul_f32 v[60:61], v[60:61], v[62:63]
	v_pk_add_f32 v[66:67], v[66:67], 1.0 op_sel_hi:[1,0]
	v_pk_mul_f32 v[56:57], v[60:61], v[56:57]
	v_cvt_pk_bf16_f32 v58, v56, v57
	v_rcp_f32_e32 v57, v67
	v_mul_f32_e32 v60, 0xbfb8aa3b, v52
	v_mul_f32_e32 v61, 0xbfb8aa3b, v53
	v_exp_f32_e32 v60, v60
	v_exp_f32_e32 v61, v61
	v_rcp_f32_e32 v56, v66
	s_nop 0
	v_pk_mul_f32 v[54:55], v[54:55], v[56:57]
	v_pk_add_f32 v[60:61], v[60:61], 1.0 op_sel_hi:[1,0]
	v_pk_mul_f32 v[50:51], v[54:55], v[50:51]
	v_cvt_pk_bf16_f32 v57, v50, v51
	v_rcp_f32_e32 v51, v61
	v_rcp_f32_e32 v50, v60
	s_nop 0
	v_pk_mul_f32 v[50:51], v[52:53], v[50:51]
	s_nop 0
	v_pk_mul_f32 v[48:49], v[50:51], v[48:49]
	s_nop 0
	v_cvt_pk_bf16_f32 v56, v48, v49
	v_mov_b64_e32 v[48:49], s[2:3]
	v_mad_i64_i32 v[48:49], s[40:41], v64, s63, v[48:49]
	v_lshl_add_u64 v[48:49], v[140:141], 1, v[48:49]
	global_store_dwordx4 v[48:49], v[56:59], off nt
; __device__ __forceinline__ unsigned cvt_pk_bf16(float lo, float hi) { const f32x2 v = {lo, hi}; return __builtin_bit_cast(unsigned, __builtin_convertvector(v, bf16x2_t)); }
; __device__ __forceinline__ float silu(float x) { return x * sigm(x); }
;     __device__ __forceinline__ void operator()(AccRef acc, const Unit& u, int wr, int wc, int fr, int fq) const {
;     ...
;             for (int m = 0; m < 4; ++m) {
;                 const f32x4 g0 = acc[ai][0][m][0], g1 = acc[ai][0][m][1], u0 = acc[ai][1][m][0], u1 = acc[ai][1][m][1];
;                 u32x4 w;
;                 w.x = cvt_pk_bf16(silu(g0[0]) * u0[0], silu(g0[1]) * u0[1]); w.y = cvt_pk_bf16(silu(g0[2]) * u0[2], silu(g0[3]) * u0[3]);
;                 w.z = cvt_pk_bf16(silu(g1[0]) * u1[0], silu(g1[1]) * u1[1]); w.w = cvt_pk_bf16(silu(g1[2]) * u1[2], silu(g1[3]) * u1[3]);
;                 if (EPI_ROWS(ai, m) < MT) *(u32x4*)(O + (size_t)EPI_ROWS(ai, m) * FF + col0) = w;
.LBB0_176:
	s_or_b64 exec, exec, s[26:27]
	v_add_u32_e32 v48, 0x90, v148
	v_cmp_gt_i32_e32 vcc, s62, v48
	s_and_saveexec_b64 s[26:27], vcc
	s_cbranch_execz .LBB0_178
	v_mul_f32_e32 v49, 0xbfb8aa3b, v46
	v_exp_f32_e32 v50, v49
	v_mul_f32_e32 v49, 0xbfb8aa3b, v47
	v_exp_f32_e32 v51, v49
	s_nop 0
	v_pk_add_f32 v[50:51], v[50:51], 1.0 op_sel_hi:[1,0]
	s_nop 0
	v_rcp_f32_e32 v51, v51
	v_mul_f32_e32 v52, 0xbfb8aa3b, v44
	v_mul_f32_e32 v53, 0xbfb8aa3b, v45
	v_exp_f32_e32 v52, v52
	v_exp_f32_e32 v53, v53
	v_rcp_f32_e32 v50, v50
	s_nop 0
	v_pk_mul_f32 v[46:47], v[46:47], v[50:51]
	v_pk_add_f32 v[52:53], v[52:53], 1.0 op_sel_hi:[1,0]
	v_pk_mul_f32 v[42:43], v[46:47], v[42:43]
	v_cvt_pk_bf16_f32 v43, v42, v43
	v_rcp_f32_e32 v47, v53
	v_mul_f32_e32 v49, 0xbfb8aa3b, v38
	v_exp_f32_e32 v50, v49
	v_mul_f32_e32 v49, 0xbfb8aa3b, v39
	v_exp_f32_e32 v51, v49
	v_rcp_f32_e32 v46, v52
	s_nop 0
	v_pk_mul_f32 v[44:45], v[44:45], v[46:47]
	v_pk_add_f32 v[50:51], v[50:51], 1.0 op_sel_hi:[1,0]
	v_pk_mul_f32 v[40:41], v[44:45], v[40:41]
	v_cvt_pk_bf16_f32 v42, v40, v41
	v_rcp_f32_e32 v41, v51
	v_mul_f32_e32 v44, 0xbfb8aa3b, v36
	v_mul_f32_e32 v45, 0xbfb8aa3b, v37
	v_exp_f32_e32 v44, v44
	v_exp_f32_e32 v45, v45
	v_rcp_f32_e32 v40, v50
	s_nop 0
	v_pk_mul_f32 v[38:39], v[38:39], v[40:41]
	v_pk_add_f32 v[44:45], v[44:45], 1.0 op_sel_hi:[1,0]
	v_pk_mul_f32 v[34:35], v[38:39], v[34:35]
	v_cvt_pk_bf16_f32 v41, v34, v35
	v_rcp_f32_e32 v35, v45
	v_rcp_f32_e32 v34, v44
	s_nop 0
	v_pk_mul_f32 v[34:35], v[36:37], v[34:35]
	s_nop 0
	v_pk_mul_f32 v[32:33], v[34:35], v[32:33]
	s_nop 0
	v_cvt_pk_bf16_f32 v40, v32, v33
	v_mov_b64_e32 v[32:33], s[2:3]
	v_mad_i64_i32 v[32:33], s[40:41], v48, s63, v[32:33]
	v_lshl_add_u64 v[32:33], v[140:141], 1, v[32:33]
	global_store_dwordx4 v[32:33], v[40:43], off nt
.LBB0_178:
	s_or_b64 exec, exec, s[26:27]
	v_add_u32_e32 v32, 0xa0, v148
	v_cmp_gt_i32_e32 vcc, s62, v32
	s_and_saveexec_b64 s[26:27], vcc
	s_cbranch_execz .LBB0_180
	v_mul_f32_e32 v33, 0xbfb8aa3b, v30
	v_exp_f32_e32 v34, v33
	v_mul_f32_e32 v33, 0xbfb8aa3b, v31
	v_exp_f32_e32 v35, v33
	s_nop 0
	v_pk_add_f32 v[34:35], v[34:35], 1.0 op_sel_hi:[1,0]
	s_nop 0
	v_rcp_f32_e32 v35, v35
	v_mul_f32_e32 v36, 0xbfb8aa3b, v28
	v_mul_f32_e32 v37, 0xbfb8aa3b, v29
	v_exp_f32_e32 v36, v36
	v_exp_f32_e32 v37, v37
	v_rcp_f32_e32 v34, v34
	s_nop 0
	v_pk_mul_f32 v[30:31], v[30:31], v[34:35]
	v_pk_add_f32 v[36:37], v[36:37], 1.0 op_sel_hi:[1,0]
	v_pk_mul_f32 v[26:27], v[30:31], v[26:27]
	v_cvt_pk_bf16_f32 v27, v26, v27
	v_rcp_f32_e32 v31, v37
	v_mul_f32_e32 v33, 0xbfb8aa3b, v22
	v_exp_f32_e32 v34, v33
	v_mul_f32_e32 v33, 0xbfb8aa3b, v23
	v_exp_f32_e32 v35, v33
	v_rcp_f32_e32 v30, v36
	s_nop 0
	v_pk_mul_f32 v[28:29], v[28:29], v[30:31]
	v_pk_add_f32 v[34:35], v[34:35], 1.0 op_sel_hi:[1,0]
	v_pk_mul_f32 v[24:25], v[28:29], v[24:25]
	v_cvt_pk_bf16_f32 v26, v24, v25
	v_rcp_f32_e32 v25, v35
	v_mul_f32_e32 v28, 0xbfb8aa3b, v20
	v_mul_f32_e32 v29, 0xbfb8aa3b, v21
	v_exp_f32_e32 v28, v28
	v_exp_f32_e32 v29, v29
	v_rcp_f32_e32 v24, v34
	s_nop 0
	v_pk_mul_f32 v[22:23], v[22:23], v[24:25]
	v_pk_add_f32 v[28:29], v[28:29], 1.0 op_sel_hi:[1,0]
	v_pk_mul_f32 v[18:19], v[22:23], v[18:19]
	v_cvt_pk_bf16_f32 v25, v18, v19
	v_rcp_f32_e32 v19, v29
	v_rcp_f32_e32 v18, v28
	s_nop 0
	v_pk_mul_f32 v[18:19], v[20:21], v[18:19]
	s_nop 0
	v_pk_mul_f32 v[16:17], v[18:19], v[16:17]
	s_nop 0
	v_cvt_pk_bf16_f32 v24, v16, v17
	v_mov_b64_e32 v[16:17], s[2:3]
	v_mad_i64_i32 v[16:17], s[40:41], v32, s63, v[16:17]
	v_lshl_add_u64 v[16:17], v[140:141], 1, v[16:17]
	global_store_dwordx4 v[16:17], v[24:27], off nt
.LBB0_180:
	s_or_b64 exec, exec, s[26:27]
	v_add_u32_e32 v16, 0xb0, v148
	v_cmp_gt_i32_e32 vcc, s62, v16
	s_and_saveexec_b64 s[26:27], vcc
	s_cbranch_execz .LBB0_182
	v_mul_f32_e32 v17, 0xbfb8aa3b, v14
	v_exp_f32_e32 v18, v17
	v_mul_f32_e32 v17, 0xbfb8aa3b, v15
	v_exp_f32_e32 v19, v17
	s_nop 0
	v_pk_add_f32 v[18:19], v[18:19], 1.0 op_sel_hi:[1,0]
	s_nop 0
	v_rcp_f32_e32 v19, v19
	v_mul_f32_e32 v20, 0xbfb8aa3b, v12
	v_mul_f32_e32 v21, 0xbfb8aa3b, v13
	v_exp_f32_e32 v20, v20
	v_exp_f32_e32 v21, v21
	v_rcp_f32_e32 v18, v18
	s_nop 0
	v_pk_mul_f32 v[14:15], v[14:15], v[18:19]
	v_pk_add_f32 v[20:21], v[20:21], 1.0 op_sel_hi:[1,0]
	v_pk_mul_f32 v[10:11], v[14:15], v[10:11]
	v_cvt_pk_bf16_f32 v11, v10, v11
	v_rcp_f32_e32 v15, v21
	v_mul_f32_e32 v17, 0xbfb8aa3b, v6
	v_exp_f32_e32 v18, v17
	v_mul_f32_e32 v17, 0xbfb8aa3b, v7
	v_exp_f32_e32 v19, v17
	v_rcp_f32_e32 v14, v20
	s_nop 0
	v_pk_mul_f32 v[12:13], v[12:13], v[14:15]
	v_pk_add_f32 v[18:19], v[18:19], 1.0 op_sel_hi:[1,0]
	v_pk_mul_f32 v[8:9], v[12:13], v[8:9]
	v_cvt_pk_bf16_f32 v10, v8, v9
	v_rcp_f32_e32 v9, v19
	v_mul_f32_e32 v12, 0xbfb8aa3b, v4
	v_mul_f32_e32 v13, 0xbfb8aa3b, v5
	v_exp_f32_e32 v12, v12
	v_exp_f32_e32 v13, v13
	v_rcp_f32_e32 v8, v18
	s_nop 0
	v_pk_mul_f32 v[6:7], v[6:7], v[8:9]
	v_pk_add_f32 v[12:13], v[12:13], 1.0 op_sel_hi:[1,0]
	v_pk_mul_f32 v[2:3], v[6:7], v[2:3]
	v_cvt_pk_bf16_f32 v9, v2, v3
	v_rcp_f32_e32 v3, v13
	v_rcp_f32_e32 v2, v12
	s_nop 0
	v_pk_mul_f32 v[2:3], v[4:5], v[2:3]
	s_nop 0
	v_pk_mul_f32 v[0:1], v[2:3], v[0:1]
	s_nop 0
	v_cvt_pk_bf16_f32 v8, v0, v1
	v_mov_b64_e32 v[0:1], s[2:3]
	v_mad_i64_i32 v[0:1], s[40:41], v16, s63, v[0:1]
	v_lshl_add_u64 v[0:1], v[140:141], 1, v[0:1]
	global_store_dwordx4 v[0:1], v[8:11], off nt

; __device__ __forceinline__ u32x2 pack4(f32x4 v) { u32x2 r; r.x = cvt_pk_bf16(v.x, v.y); r.y = cvt_pk_bf16(v.z, v.w); return r; }
;     __device__ __forceinline__ void operator()(AccRef acc, const Unit& u, int wr, int wc, int fr, int fq) const {
;         const bool isk = u.pn < 4; float* o = isk ? ok : ov; const int col0 = (u.pn & 3) * BM + wc * 32 + 4 * fq;
; #pragma unroll
;         for (int ai = 0; ai < 2; ++ai)
; #pragma unroll
;             for (int m = 0; m < 4; ++m) { const size_t off = (size_t)EPI_ROWS(ai, m) * D + col0;
; #pragma unroll
;                 for (int bj = 0; bj < 2; ++bj)
; #pragma unroll
;                     for (int n = 0; n < 2; ++n) { const f32x4 v = acc[ai][bj][m][n]; *(f32x4*)(o + off + bj * HALF + n * 16) = v;
;                         if (isk) *(u32x2*)(KB + off + bj * HALF + n * 16) = pack4(v); } }
.LBB0_208:
	s_cmp_gt_i32 s28, 3
	v_readlane_b32 s64, v229, 48
	s_cselect_b64 s[40:41], -1, 0
	s_cmp_lt_i32 s28, 4
	s_mov_b32 s15, 0x4080000
	v_readlane_b32 s78, v229, 62
	v_readlane_b32 s79, v229, 63
	s_cselect_b32 s15, s15, 0x4880000
	s_mov_b64 s[30:31], s[78:79]
	s_add_u32 s44, s30, s15
	s_addc_u32 s45, s31, 0
	s_lshl_b32 s15, s28, 8
	v_lshl_add_u32 v136, s26, 8, v142
	s_and_b32 s15, s15, 0x300
	v_ashrrev_i32_e32 v137, 31, v136
	v_or_b32_e32 v148, s15, v144
	v_lshlrev_b64 v[140:141], 10, v[136:137]
	v_or_b32_e32 v140, v140, v148
	v_lshl_add_u64 v[138:139], v[140:141], 2, s[44:45]
	s_mov_b64 s[26:27], -1
	s_and_b64 vcc, exec, s[40:41]
	v_readlane_b32 s65, v229, 49
	v_readlane_b32 s66, v229, 50
	v_readlane_b32 s67, v229, 51
	v_readlane_b32 s68, v229, 52
	v_readlane_b32 s69, v229, 53
	v_readlane_b32 s70, v229, 54
	v_readlane_b32 s71, v229, 55
	v_readlane_b32 s72, v229, 56
	v_readlane_b32 s73, v229, 57
	v_readlane_b32 s74, v229, 58
	v_readlane_b32 s75, v229, 59
	v_readlane_b32 s76, v229, 60
	v_readlane_b32 s77, v229, 61
	global_store_dwordx4 v[138:139], v[124:127], off nt
	s_cbranch_vccnz .LBB0_248
	s_andn2_b64 vcc, exec, s[26:27]
	v_lshl_add_u64 v[140:141], v[140:141], 1, s[2:3]
	s_cbranch_vccz .LBB0_249
.LBB0_210:
	s_mov_b64 s[26:27], -1
	s_and_b64 vcc, exec, s[40:41]
	global_store_dwordx4 v[138:139], v[116:119], off offset:512 nt
	s_cbranch_vccnz .LBB0_250

; __device__ __forceinline__ u32x2 pack4(f32x4 v) { u32x2 r; r.x = cvt_pk_bf16(v.x, v.y); r.y = cvt_pk_bf16(v.z, v.w); return r; }
;     __device__ __forceinline__ void operator()(AccRef acc, const Unit& u, int wr, int wc, int fr, int fq) const {
;     ...
;                 for (int bj = 0; bj < 2; ++bj)
; #pragma unroll
;                     for (int n = 0; n < 2; ++n) { const f32x4 v = acc[ai][bj][m][n]; *(f32x4*)(o + off + bj * HALF + n * 16) = v;
;                         if (isk) *(u32x2*)(KB + off + bj * HALF + n * 16) = pack4(v); } }
.LBB0_212:
	v_cvt_pk_bf16_f32 v116, v116, v117
	v_cvt_pk_bf16_f32 v117, v118, v119
	global_store_dwordx2 v[140:141], v[116:117], off offset:256
	global_store_dwordx4 v[138:139], v[112:115], off offset:576 nt
	s_nop 1
	v_cvt_pk_bf16_f32 v112, v112, v113
	v_cvt_pk_bf16_f32 v113, v114, v115
	global_store_dwordx2 v[140:141], v[112:113], off offset:288
.LBB0_213:
	v_or_b32_e32 v112, 16, v136
	v_ashrrev_i32_e32 v113, 31, v112
	v_lshlrev_b64 v[114:115], 10, v[112:113]
	v_or_b32_e32 v114, v114, v148
	v_lshl_add_u64 v[112:113], v[114:115], 2, s[44:45]
	s_mov_b64 s[26:27], -1
	s_and_b64 vcc, exec, s[40:41]
	global_store_dwordx4 v[112:113], v[108:111], off nt
	s_cbranch_vccnz .LBB0_251
	s_andn2_b64 vcc, exec, s[26:27]
	v_lshl_add_u64 v[114:115], v[114:115], 1, s[2:3]
	s_cbranch_vccz .LBB0_252
.LBB0_215:
	s_mov_b64 s[26:27], -1
	s_and_b64 vcc, exec, s[40:41]
	global_store_dwordx4 v[112:113], v[100:103], off offset:512 nt
	s_cbranch_vccnz .LBB0_253

; __device__ __forceinline__ u32x2 pack4(f32x4 v) { u32x2 r; r.x = cvt_pk_bf16(v.x, v.y); r.y = cvt_pk_bf16(v.z, v.w); return r; }
;     __device__ __forceinline__ void operator()(AccRef acc, const Unit& u, int wr, int wc, int fr, int fq) const {
;     ...
;                 for (int bj = 0; bj < 2; ++bj)
; #pragma unroll
;                     for (int n = 0; n < 2; ++n) { const f32x4 v = acc[ai][bj][m][n]; *(f32x4*)(o + off + bj * HALF + n * 16) = v;
;                         if (isk) *(u32x2*)(KB + off + bj * HALF + n * 16) = pack4(v); } }
.LBB0_217:
	v_cvt_pk_bf16_f32 v100, v100, v101
	v_cvt_pk_bf16_f32 v101, v102, v103
	global_store_dwordx2 v[114:115], v[100:101], off offset:256
	global_store_dwordx4 v[112:113], v[96:99], off offset:576 nt
	s_nop 1
	v_cvt_pk_bf16_f32 v96, v96, v97
	v_cvt_pk_bf16_f32 v97, v98, v99
	global_store_dwordx2 v[114:115], v[96:97], off offset:288
.LBB0_218:
	v_or_b32_e32 v96, 32, v136
	v_ashrrev_i32_e32 v97, 31, v96
	v_lshlrev_b64 v[98:99], 10, v[96:97]
	v_or_b32_e32 v98, v98, v148
	v_lshl_add_u64 v[96:97], v[98:99], 2, s[44:45]
	s_mov_b64 s[26:27], -1
	s_and_b64 vcc, exec, s[40:41]
	global_store_dwordx4 v[96:97], v[92:95], off nt
	s_cbranch_vccnz .LBB0_254
	s_andn2_b64 vcc, exec, s[26:27]
	v_lshl_add_u64 v[98:99], v[98:99], 1, s[2:3]
	s_cbranch_vccz .LBB0_255
.LBB0_220:
	s_mov_b64 s[26:27], -1
	s_and_b64 vcc, exec, s[40:41]
	global_store_dwordx4 v[96:97], v[84:87], off offset:512 nt
	s_cbranch_vccnz .LBB0_256

; __device__ __forceinline__ u32x2 pack4(f32x4 v) { u32x2 r; r.x = cvt_pk_bf16(v.x, v.y); r.y = cvt_pk_bf16(v.z, v.w); return r; }
;     __device__ __forceinline__ void operator()(AccRef acc, const Unit& u, int wr, int wc, int fr, int fq) const {
;     ...
;                 for (int bj = 0; bj < 2; ++bj)
; #pragma unroll
;                     for (int n = 0; n < 2; ++n) { const f32x4 v = acc[ai][bj][m][n]; *(f32x4*)(o + off + bj * HALF + n * 16) = v;
;                         if (isk) *(u32x2*)(KB + off + bj * HALF + n * 16) = pack4(v); } }
.LBB0_222:
	v_cvt_pk_bf16_f32 v84, v84, v85
	v_cvt_pk_bf16_f32 v85, v86, v87
	global_store_dwordx2 v[98:99], v[84:85], off offset:256
	global_store_dwordx4 v[96:97], v[80:83], off offset:576 nt
	s_nop 1
	v_cvt_pk_bf16_f32 v80, v80, v81
	v_cvt_pk_bf16_f32 v81, v82, v83
	global_store_dwordx2 v[98:99], v[80:81], off offset:288
.LBB0_223:
	v_or_b32_e32 v80, 48, v136
	v_ashrrev_i32_e32 v81, 31, v80
	v_lshlrev_b64 v[82:83], 10, v[80:81]
	v_or_b32_e32 v82, v82, v148
	v_lshl_add_u64 v[80:81], v[82:83], 2, s[44:45]
	s_mov_b64 s[26:27], -1
	s_and_b64 vcc, exec, s[40:41]
	global_store_dwordx4 v[80:81], v[76:79], off nt
	s_cbranch_vccnz .LBB0_257
	s_andn2_b64 vcc, exec, s[26:27]
	v_lshl_add_u64 v[82:83], v[82:83], 1, s[2:3]
	s_cbranch_vccz .LBB0_258
.LBB0_225:
	s_mov_b64 s[26:27], -1
	s_and_b64 vcc, exec, s[40:41]
	global_store_dwordx4 v[80:81], v[68:71], off offset:512 nt
	s_cbranch_vccnz .LBB0_259

; __device__ __forceinline__ u32x2 pack4(f32x4 v) { u32x2 r; r.x = cvt_pk_bf16(v.x, v.y); r.y = cvt_pk_bf16(v.z, v.w); return r; }
;     __device__ __forceinline__ void operator()(AccRef acc, const Unit& u, int wr, int wc, int fr, int fq) const {
;     ...
;                 for (int bj = 0; bj < 2; ++bj)
; #pragma unroll
;                     for (int n = 0; n < 2; ++n) { const f32x4 v = acc[ai][bj][m][n]; *(f32x4*)(o + off + bj * HALF + n * 16) = v;
;                         if (isk) *(u32x2*)(KB + off + bj * HALF + n * 16) = pack4(v); } }
.LBB0_227:
	v_cvt_pk_bf16_f32 v68, v68, v69
	v_cvt_pk_bf16_f32 v69, v70, v71
	global_store_dwordx2 v[82:83], v[68:69], off offset:256
	global_store_dwordx4 v[80:81], v[64:67], off offset:576 nt
	s_nop 1
	v_cvt_pk_bf16_f32 v64, v64, v65
	v_cvt_pk_bf16_f32 v65, v66, v67
	global_store_dwordx2 v[82:83], v[64:65], off offset:288
.LBB0_228:
	v_add_u32_e32 v64, 0x80, v136
	v_ashrrev_i32_e32 v65, 31, v64
	v_lshlrev_b64 v[66:67], 10, v[64:65]
	v_or_b32_e32 v66, v66, v148
	v_lshl_add_u64 v[64:65], v[66:67], 2, s[44:45]
	s_mov_b64 s[26:27], -1
	s_and_b64 vcc, exec, s[40:41]
	global_store_dwordx4 v[64:65], v[60:63], off nt
	s_cbranch_vccnz .LBB0_260
	s_andn2_b64 vcc, exec, s[26:27]
	v_lshl_add_u64 v[66:67], v[66:67], 1, s[2:3]
	s_cbranch_vccz .LBB0_261
.LBB0_230:
	s_mov_b64 s[26:27], -1
	s_and_b64 vcc, exec, s[40:41]
	global_store_dwordx4 v[64:65], v[52:55], off offset:512 nt
	s_cbranch_vccnz .LBB0_262

; __device__ __forceinline__ u32x2 pack4(f32x4 v) { u32x2 r; r.x = cvt_pk_bf16(v.x, v.y); r.y = cvt_pk_bf16(v.z, v.w); return r; }
;     __device__ __forceinline__ void operator()(AccRef acc, const Unit& u, int wr, int wc, int fr, int fq) const {
;     ...
;                 for (int bj = 0; bj < 2; ++bj)
; #pragma unroll
;                     for (int n = 0; n < 2; ++n) { const f32x4 v = acc[ai][bj][m][n]; *(f32x4*)(o + off + bj * HALF + n * 16) = v;
;                         if (isk) *(u32x2*)(KB + off + bj * HALF + n * 16) = pack4(v); } }
.LBB0_232:
	v_cvt_pk_bf16_f32 v52, v52, v53
	v_cvt_pk_bf16_f32 v53, v54, v55
	global_store_dwordx2 v[66:67], v[52:53], off offset:256
	global_store_dwordx4 v[64:65], v[48:51], off offset:576 nt
	s_nop 1
	v_cvt_pk_bf16_f32 v48, v48, v49
	v_cvt_pk_bf16_f32 v49, v50, v51
	global_store_dwordx2 v[66:67], v[48:49], off offset:288
.LBB0_233:
	v_add_u32_e32 v48, 0x90, v136
	v_ashrrev_i32_e32 v49, 31, v48
	v_lshlrev_b64 v[50:51], 10, v[48:49]
	v_or_b32_e32 v50, v50, v148
	v_lshl_add_u64 v[48:49], v[50:51], 2, s[44:45]
	s_mov_b64 s[26:27], -1
	s_and_b64 vcc, exec, s[40:41]
	global_store_dwordx4 v[48:49], v[44:47], off nt
	s_cbranch_vccnz .LBB0_263
	s_andn2_b64 vcc, exec, s[26:27]
	v_lshl_add_u64 v[50:51], v[50:51], 1, s[2:3]
	s_cbranch_vccz .LBB0_264
.LBB0_235:
	s_mov_b64 s[26:27], -1
	s_and_b64 vcc, exec, s[40:41]
	global_store_dwordx4 v[48:49], v[36:39], off offset:512 nt
	s_cbranch_vccnz .LBB0_265

; __device__ __forceinline__ u32x2 pack4(f32x4 v) { u32x2 r; r.x = cvt_pk_bf16(v.x, v.y); r.y = cvt_pk_bf16(v.z, v.w); return r; }
;     __device__ __forceinline__ void operator()(AccRef acc, const Unit& u, int wr, int wc, int fr, int fq) const {
;     ...
;                 for (int bj = 0; bj < 2; ++bj)
; #pragma unroll
;                     for (int n = 0; n < 2; ++n) { const f32x4 v = acc[ai][bj][m][n]; *(f32x4*)(o + off + bj * HALF + n * 16) = v;
;                         if (isk) *(u32x2*)(KB + off + bj * HALF + n * 16) = pack4(v); } }
.LBB0_237:
	v_cvt_pk_bf16_f32 v36, v36, v37
	v_cvt_pk_bf16_f32 v37, v38, v39
	global_store_dwordx2 v[50:51], v[36:37], off offset:256
	global_store_dwordx4 v[48:49], v[32:35], off offset:576 nt
	s_nop 1
	v_cvt_pk_bf16_f32 v32, v32, v33
	v_cvt_pk_bf16_f32 v33, v34, v35
	global_store_dwordx2 v[50:51], v[32:33], off offset:288
.LBB0_238:
	v_add_u32_e32 v32, 0xa0, v136
	v_ashrrev_i32_e32 v33, 31, v32
	v_lshlrev_b64 v[34:35], 10, v[32:33]
	v_or_b32_e32 v34, v34, v148
	v_lshl_add_u64 v[32:33], v[34:35], 2, s[44:45]
	s_mov_b64 s[26:27], -1
	s_and_b64 vcc, exec, s[40:41]
	global_store_dwordx4 v[32:33], v[28:31], off nt
	s_cbranch_vccnz .LBB0_266
	s_andn2_b64 vcc, exec, s[26:27]
	v_lshl_add_u64 v[34:35], v[34:35], 1, s[2:3]
	s_cbranch_vccz .LBB0_267
.LBB0_240:
	s_mov_b64 s[26:27], -1
	s_and_b64 vcc, exec, s[40:41]
	global_store_dwordx4 v[32:33], v[20:23], off offset:512 nt
	s_cbranch_vccnz .LBB0_268

; __device__ __forceinline__ u32x2 pack4(f32x4 v) { u32x2 r; r.x = cvt_pk_bf16(v.x, v.y); r.y = cvt_pk_bf16(v.z, v.w); return r; }
;     __device__ __forceinline__ void operator()(AccRef acc, const Unit& u, int wr, int wc, int fr, int fq) const {
;     ...
;                 for (int bj = 0; bj < 2; ++bj)
; #pragma unroll
;                     for (int n = 0; n < 2; ++n) { const f32x4 v = acc[ai][bj][m][n]; *(f32x4*)(o + off + bj * HALF + n * 16) = v;
;                         if (isk) *(u32x2*)(KB + off + bj * HALF + n * 16) = pack4(v); } }
.LBB0_242:
	v_cvt_pk_bf16_f32 v20, v20, v21
	v_cvt_pk_bf16_f32 v21, v22, v23
	global_store_dwordx2 v[34:35], v[20:21], off offset:256
	global_store_dwordx4 v[32:33], v[16:19], off offset:576 nt
	s_nop 1
	v_cvt_pk_bf16_f32 v16, v16, v17
	v_cvt_pk_bf16_f32 v17, v18, v19
	global_store_dwordx2 v[34:35], v[16:17], off offset:288
.LBB0_243:
	v_add_u32_e32 v16, 0xb0, v136
	v_ashrrev_i32_e32 v17, 31, v16
	v_lshlrev_b64 v[18:19], 10, v[16:17]
	v_or_b32_e32 v18, v18, v148
	v_lshl_add_u64 v[16:17], v[18:19], 2, s[44:45]
	s_mov_b64 s[26:27], -1
	s_and_b64 vcc, exec, s[40:41]
	global_store_dwordx4 v[16:17], v[12:15], off nt
	s_cbranch_vccnz .LBB0_269
	s_andn2_b64 vcc, exec, s[26:27]
	v_lshl_add_u64 v[18:19], v[18:19], 1, s[2:3]
	s_cbranch_vccz .LBB0_270
.LBB0_245:
	s_mov_b64 s[26:27], -1
	s_and_b64 vcc, exec, s[40:41]
	global_store_dwordx4 v[16:17], v[4:7], off offset:512 nt
	s_cbranch_vccnz .LBB0_271

; __device__ __forceinline__ u32x2 pack4(f32x4 v) { u32x2 r; r.x = cvt_pk_bf16(v.x, v.y); r.y = cvt_pk_bf16(v.z, v.w); return r; }
;     __device__ __forceinline__ void operator()(AccRef acc, const Unit& u, int wr, int wc, int fr, int fq) const {
;     ...
;             for (int m = 0; m < 4; ++m) { const size_t off = (size_t)EPI_ROWS(ai, m) * D + col0;
; #pragma unroll
;                 for (int bj = 0; bj < 2; ++bj)
; #pragma unroll
;                     for (int n = 0; n < 2; ++n) { const f32x4 v = acc[ai][bj][m][n]; *(f32x4*)(o + off + bj * HALF + n * 16) = v;
;                         if (isk) *(u32x2*)(KB + off + bj * HALF + n * 16) = pack4(v); } }
.LBB0_248:
	global_store_dwordx4 v[138:139], v[120:123], off offset:64 nt
	v_lshl_add_u64 v[140:141], v[140:141], 1, s[2:3]
	s_cbranch_execnz .LBB0_210
.LBB0_249:
	v_cvt_pk_bf16_f32 v124, v124, v125
	v_cvt_pk_bf16_f32 v125, v126, v127
	global_store_dwordx2 v[140:141], v[124:125], off
	global_store_dwordx4 v[138:139], v[120:123], off offset:64 nt
	s_nop 1
	v_cvt_pk_bf16_f32 v120, v120, v121
	v_cvt_pk_bf16_f32 v121, v122, v123
	global_store_dwordx2 v[140:141], v[120:121], off offset:32
	s_mov_b64 s[26:27], -1
	s_and_b64 vcc, exec, s[40:41]
	global_store_dwordx4 v[138:139], v[116:119], off offset:512 nt
	s_cbranch_vccz .LBB0_211
.LBB0_250:
	global_store_dwordx4 v[138:139], v[112:115], off offset:576 nt
	s_cbranch_execz .LBB0_212
	s_branch .LBB0_213
.LBB0_251:
	global_store_dwordx4 v[112:113], v[104:107], off offset:64 nt
	v_lshl_add_u64 v[114:115], v[114:115], 1, s[2:3]
	s_cbranch_execnz .LBB0_215
.LBB0_252:
	v_cvt_pk_bf16_f32 v108, v108, v109
	v_cvt_pk_bf16_f32 v109, v110, v111
	global_store_dwordx2 v[114:115], v[108:109], off
	global_store_dwordx4 v[112:113], v[104:107], off offset:64 nt
	s_nop 1
	v_cvt_pk_bf16_f32 v104, v104, v105
	v_cvt_pk_bf16_f32 v105, v106, v107
	global_store_dwordx2 v[114:115], v[104:105], off offset:32
	s_mov_b64 s[26:27], -1
	s_and_b64 vcc, exec, s[40:41]
	global_store_dwordx4 v[112:113], v[100:103], off offset:512 nt
	s_cbranch_vccz .LBB0_216
.LBB0_253:
	global_store_dwordx4 v[112:113], v[96:99], off offset:576 nt
	s_cbranch_execz .LBB0_217
	s_branch .LBB0_218
.LBB0_254:
	global_store_dwordx4 v[96:97], v[88:91], off offset:64 nt
	v_lshl_add_u64 v[98:99], v[98:99], 1, s[2:3]
	s_cbranch_execnz .LBB0_220
.LBB0_255:
	v_cvt_pk_bf16_f32 v92, v92, v93
	v_cvt_pk_bf16_f32 v93, v94, v95
	global_store_dwordx2 v[98:99], v[92:93], off
	global_store_dwordx4 v[96:97], v[88:91], off offset:64 nt
	s_nop 1
	v_cvt_pk_bf16_f32 v88, v88, v89
	v_cvt_pk_bf16_f32 v89, v90, v91
	global_store_dwordx2 v[98:99], v[88:89], off offset:32
	s_mov_b64 s[26:27], -1
	s_and_b64 vcc, exec, s[40:41]
	global_store_dwordx4 v[96:97], v[84:87], off offset:512 nt
	s_cbranch_vccz .LBB0_221
.LBB0_256:
	global_store_dwordx4 v[96:97], v[80:83], off offset:576 nt
	s_cbranch_execz .LBB0_222
	s_branch .LBB0_223
.LBB0_257:
	global_store_dwordx4 v[80:81], v[72:75], off offset:64 nt
	v_lshl_add_u64 v[82:83], v[82:83], 1, s[2:3]
	s_cbranch_execnz .LBB0_225
.LBB0_258:
	v_cvt_pk_bf16_f32 v76, v76, v77
	v_cvt_pk_bf16_f32 v77, v78, v79
	global_store_dwordx2 v[82:83], v[76:77], off
	global_store_dwordx4 v[80:81], v[72:75], off offset:64 nt
	s_nop 1
	v_cvt_pk_bf16_f32 v72, v72, v73
	v_cvt_pk_bf16_f32 v73, v74, v75
	global_store_dwordx2 v[82:83], v[72:73], off offset:32
	s_mov_b64 s[26:27], -1
	s_and_b64 vcc, exec, s[40:41]
	global_store_dwordx4 v[80:81], v[68:71], off offset:512 nt
	s_cbranch_vccz .LBB0_226
.LBB0_259:
	global_store_dwordx4 v[80:81], v[64:67], off offset:576 nt
	s_cbranch_execz .LBB0_227
	s_branch .LBB0_228
.LBB0_260:
	global_store_dwordx4 v[64:65], v[56:59], off offset:64 nt
	v_lshl_add_u64 v[66:67], v[66:67], 1, s[2:3]
	s_cbranch_execnz .LBB0_230
.LBB0_261:
	v_cvt_pk_bf16_f32 v60, v60, v61
	v_cvt_pk_bf16_f32 v61, v62, v63
	global_store_dwordx2 v[66:67], v[60:61], off
	global_store_dwordx4 v[64:65], v[56:59], off offset:64 nt
	s_nop 1
	v_cvt_pk_bf16_f32 v56, v56, v57
	v_cvt_pk_bf16_f32 v57, v58, v59
	global_store_dwordx2 v[66:67], v[56:57], off offset:32
	s_mov_b64 s[26:27], -1
	s_and_b64 vcc, exec, s[40:41]
	global_store_dwordx4 v[64:65], v[52:55], off offset:512 nt
	s_cbranch_vccz .LBB0_231
.LBB0_262:
	global_store_dwordx4 v[64:65], v[48:51], off offset:576 nt
	s_cbranch_execz .LBB0_232
	s_branch .LBB0_233
.LBB0_263:
	global_store_dwordx4 v[48:49], v[40:43], off offset:64 nt
	v_lshl_add_u64 v[50:51], v[50:51], 1, s[2:3]
	s_cbranch_execnz .LBB0_235
.LBB0_264:
	v_cvt_pk_bf16_f32 v44, v44, v45
	v_cvt_pk_bf16_f32 v45, v46, v47
	global_store_dwordx2 v[50:51], v[44:45], off
	global_store_dwordx4 v[48:49], v[40:43], off offset:64 nt
	s_nop 1
	v_cvt_pk_bf16_f32 v40, v40, v41
	v_cvt_pk_bf16_f32 v41, v42, v43
	global_store_dwordx2 v[50:51], v[40:41], off offset:32
	s_mov_b64 s[26:27], -1
	s_and_b64 vcc, exec, s[40:41]
	global_store_dwordx4 v[48:49], v[36:39], off offset:512 nt
	s_cbranch_vccz .LBB0_236
.LBB0_265:
	global_store_dwordx4 v[48:49], v[32:35], off offset:576 nt
	s_cbranch_execz .LBB0_237
	s_branch .LBB0_238
.LBB0_266:
	global_store_dwordx4 v[32:33], v[24:27], off offset:64 nt
	v_lshl_add_u64 v[34:35], v[34:35], 1, s[2:3]
	s_cbranch_execnz .LBB0_240
.LBB0_267:
	v_cvt_pk_bf16_f32 v28, v28, v29
	v_cvt_pk_bf16_f32 v29, v30, v31
	global_store_dwordx2 v[34:35], v[28:29], off
	global_store_dwordx4 v[32:33], v[24:27], off offset:64 nt
	s_nop 1
	v_cvt_pk_bf16_f32 v24, v24, v25
	v_cvt_pk_bf16_f32 v25, v26, v27
	global_store_dwordx2 v[34:35], v[24:25], off offset:32
	s_mov_b64 s[26:27], -1
	s_and_b64 vcc, exec, s[40:41]
	global_store_dwordx4 v[32:33], v[20:23], off offset:512 nt
	s_cbranch_vccz .LBB0_241
.LBB0_268:
	global_store_dwordx4 v[32:33], v[16:19], off offset:576 nt
	s_cbranch_execz .LBB0_242
	s_branch .LBB0_243
.LBB0_269:
	global_store_dwordx4 v[16:17], v[8:11], off offset:64 nt
	v_lshl_add_u64 v[18:19], v[18:19], 1, s[2:3]
	s_cbranch_execnz .LBB0_245
.LBB0_270:
	v_cvt_pk_bf16_f32 v12, v12, v13
	v_cvt_pk_bf16_f32 v13, v14, v15
	global_store_dwordx2 v[18:19], v[12:13], off
	global_store_dwordx4 v[16:17], v[8:11], off offset:64 nt
	s_nop 1
	v_cvt_pk_bf16_f32 v8, v8, v9
	v_cvt_pk_bf16_f32 v9, v10, v11
	global_store_dwordx2 v[18:19], v[8:9], off offset:32
	s_mov_b64 s[26:27], -1
	s_and_b64 vcc, exec, s[40:41]
	global_store_dwordx4 v[16:17], v[4:7], off offset:512 nt
	s_cbranch_vccz .LBB0_246
.LBB0_271:
	global_store_dwordx4 v[16:17], v[0:3], off offset:576 nt
	s_cbranch_execnz .LBB0_247
.LBB0_272:
	v_cvt_pk_bf16_f32 v4, v4, v5
	v_cvt_pk_bf16_f32 v5, v6, v7
	global_store_dwordx2 v[18:19], v[4:5], off offset:256
	global_store_dwordx4 v[16:17], v[0:3], off offset:576 nt
	s_nop 1
	v_cvt_pk_bf16_f32 v0, v0, v1
	v_cvt_pk_bf16_f32 v1, v2, v3
	global_store_dwordx2 v[18:19], v[0:1], off offset:288
	s_andn2_b64 vcc, exec, s[8:9]
	s_mov_b64 s[8:9], -1
	s_cbranch_vccnz .LBB0_197

; __device__ __forceinline__ unsigned cvt_pk_bf16(float lo, float hi) { const f32x2 v = {lo, hi}; return __builtin_bit_cast(unsigned, __builtin_convertvector(v, bf16x2_t)); }
;     __device__ __forceinline__ void operator()(AccRef acc, const Unit& u, int wr, int wc, int fr, int fq) const {
;         const int col0 = u.pn * BM + wc * 32 + 8 * fq;
; #pragma unroll
;         for (int ai = 0; ai < 2; ++ai)
; #pragma unroll
;             for (int m = 0; m < 4; ++m) { bf16_t* rowp = O + (size_t)EPI_ROWS(ai, m) * ldc + col0;
; #pragma unroll
;                 for (int bj = 0; bj < 2; ++bj) { const f32x4 v0 = acc[ai][bj][m][0] * scale, v1 = acc[ai][bj][m][1] * scale;
;                     u32x4 w; w.x = cvt_pk_bf16(v0[0], v0[1]); w.y = cvt_pk_bf16(v0[2], v0[3]); w.z = cvt_pk_bf16(v1[0], v1[1]); w.w = cvt_pk_bf16(v1[2], v1[3]);
;                     *(u32x4*)(rowp + bj * HALF) = w; } }
;     }
.LBB0_296:
	v_lshl_add_u32 v148, s20, 8, v140
	v_cvt_pk_bf16_f32 v68, v68, v69
	v_cvt_pk_bf16_f32 v69, v70, v71
	v_cvt_pk_bf16_f32 v70, v64, v65
	v_add_u32_e32 v64, 0x80, v148
	v_lshl_or_b32 v146, s61, 8, v142
	v_ashrrev_i32_e32 v149, 31, v148
	v_cvt_pk_bf16_f32 v108, v108, v109
	v_cvt_pk_bf16_f32 v109, v110, v111
	v_cvt_pk_bf16_f32 v110, v104, v105
	v_or_b32_e32 v104, 16, v148
	v_ashrrev_i32_e32 v65, 31, v64
	v_cvt_pk_bf16_f32 v44, v44, v45
	v_cvt_pk_bf16_f32 v45, v46, v47
	v_cvt_pk_bf16_f32 v46, v40, v41
	v_add_u32_e32 v40, 0x90, v148
	v_ashrrev_i32_e32 v147, 31, v146
	v_lshlrev_b64 v[150:151], 12, v[148:149]
	v_ashrrev_i32_e32 v105, 31, v104
	v_cvt_pk_bf16_f32 v92, v92, v93
	v_cvt_pk_bf16_f32 v93, v94, v95
	v_cvt_pk_bf16_f32 v94, v88, v89
	v_or_b32_e32 v88, 32, v148
	v_lshlrev_b64 v[64:65], 12, v[64:65]
	v_ashrrev_i32_e32 v41, 31, v40
	v_cvt_pk_bf16_f32 v28, v28, v29
	v_cvt_pk_bf16_f32 v29, v30, v31
	v_cvt_pk_bf16_f32 v30, v24, v25
	v_add_u32_e32 v24, 0xa0, v148
	v_lshl_add_u64 v[150:151], s[2:3], 0, v[150:151]
	v_lshlrev_b64 v[146:147], 1, v[146:147]
	v_lshlrev_b64 v[104:105], 12, v[104:105]
	v_ashrrev_i32_e32 v89, 31, v88
	v_cvt_pk_bf16_f32 v76, v76, v77
	v_cvt_pk_bf16_f32 v77, v78, v79
	v_cvt_pk_bf16_f32 v78, v72, v73
	v_or_b32_e32 v72, 48, v148
	v_lshl_add_u64 v[64:65], s[2:3], 0, v[64:65]
	v_lshlrev_b64 v[40:41], 12, v[40:41]
	v_ashrrev_i32_e32 v25, 31, v24
	v_cvt_pk_bf16_f32 v12, v12, v13
	v_cvt_pk_bf16_f32 v13, v14, v15
	v_cvt_pk_bf16_f32 v14, v8, v9
	v_add_u32_e32 v8, 0xb0, v148
	v_lshl_add_u64 v[150:151], v[150:151], 0, v[146:147]
	v_cvt_pk_bf16_f32 v111, v106, v107
	v_lshl_add_u64 v[104:105], s[2:3], 0, v[104:105]
	v_lshlrev_b64 v[88:89], 12, v[88:89]
	v_ashrrev_i32_e32 v73, 31, v72
	v_lshl_add_u64 v[64:65], v[64:65], 0, v[146:147]
	v_cvt_pk_bf16_f32 v47, v42, v43
	v_lshl_add_u64 v[40:41], s[2:3], 0, v[40:41]
	v_lshlrev_b64 v[24:25], 12, v[24:25]
	v_ashrrev_i32_e32 v9, 31, v8
	global_store_dwordx4 v[150:151], v[108:111], off offset:256 nt
	v_cvt_pk_bf16_f32 v95, v90, v91
	v_lshl_add_u64 v[88:89], s[2:3], 0, v[88:89]
	v_lshl_add_u64 v[108:109], v[104:105], 0, v[146:147]
	v_lshlrev_b64 v[72:73], 12, v[72:73]
	global_store_dwordx4 v[64:65], v[44:47], off offset:256 nt
	v_cvt_pk_bf16_f32 v31, v26, v27
	v_lshl_add_u64 v[24:25], s[2:3], 0, v[24:25]
	v_lshl_add_u64 v[44:45], v[40:41], 0, v[146:147]
	v_lshlrev_b64 v[8:9], 12, v[8:9]
	global_store_dwordx4 v[108:109], v[92:95], off offset:256 nt
	v_cvt_pk_bf16_f32 v79, v74, v75
	v_lshl_add_u64 v[72:73], s[2:3], 0, v[72:73]
	v_lshl_add_u64 v[92:93], v[88:89], 0, v[146:147]
	global_store_dwordx4 v[44:45], v[28:31], off offset:256 nt
	v_cvt_pk_bf16_f32 v15, v10, v11
	v_lshl_add_u64 v[8:9], s[2:3], 0, v[8:9]
	v_lshl_add_u64 v[28:29], v[24:25], 0, v[146:147]
	v_cvt_pk_bf16_f32 v124, v124, v125
	v_cvt_pk_bf16_f32 v125, v126, v127
	v_cvt_pk_bf16_f32 v126, v120, v121
	v_cvt_pk_bf16_f32 v127, v122, v123
	v_cvt_pk_bf16_f32 v104, v116, v117
	v_cvt_pk_bf16_f32 v105, v118, v119
	v_cvt_pk_bf16_f32 v106, v112, v113
	v_cvt_pk_bf16_f32 v107, v114, v115
	v_cvt_pk_bf16_f32 v88, v100, v101
	v_cvt_pk_bf16_f32 v89, v102, v103
	v_cvt_pk_bf16_f32 v90, v96, v97
	v_cvt_pk_bf16_f32 v91, v98, v99
	global_store_dwordx4 v[92:93], v[76:79], off offset:256 nt
	v_cvt_pk_bf16_f32 v74, v80, v81
	v_cvt_pk_bf16_f32 v75, v82, v83
	v_lshl_add_u64 v[76:77], v[72:73], 0, v[146:147]
	v_cvt_pk_bf16_f32 v72, v84, v85
	v_cvt_pk_bf16_f32 v73, v86, v87
	v_cvt_pk_bf16_f32 v71, v66, v67
	v_cvt_pk_bf16_f32 v60, v60, v61
	v_cvt_pk_bf16_f32 v61, v62, v63
	v_cvt_pk_bf16_f32 v62, v56, v57
	v_cvt_pk_bf16_f32 v63, v58, v59
	v_cvt_pk_bf16_f32 v40, v52, v53
	v_cvt_pk_bf16_f32 v41, v54, v55
	v_cvt_pk_bf16_f32 v42, v48, v49
	v_cvt_pk_bf16_f32 v43, v50, v51
	v_cvt_pk_bf16_f32 v24, v36, v37
	v_cvt_pk_bf16_f32 v25, v38, v39
	v_cvt_pk_bf16_f32 v26, v32, v33
	v_cvt_pk_bf16_f32 v27, v34, v35
	global_store_dwordx4 v[28:29], v[12:15], off offset:256 nt
	v_cvt_pk_bf16_f32 v10, v16, v17
	v_cvt_pk_bf16_f32 v11, v18, v19
	v_lshl_add_u64 v[12:13], v[8:9], 0, v[146:147]
	v_cvt_pk_bf16_f32 v8, v20, v21
	v_cvt_pk_bf16_f32 v9, v22, v23
	v_cvt_pk_bf16_f32 v4, v4, v5
	v_cvt_pk_bf16_f32 v5, v6, v7
	v_cvt_pk_bf16_f32 v6, v0, v1
	v_cvt_pk_bf16_f32 v7, v2, v3
	s_andn2_b64 vcc, exec, s[8:9]
	s_mov_b64 s[8:9], -1
	global_store_dwordx4 v[150:151], v[124:127], off nt
	global_store_dwordx4 v[108:109], v[104:107], off nt
	global_store_dwordx4 v[92:93], v[88:91], off nt
	global_store_dwordx4 v[76:77], v[72:75], off nt
	global_store_dwordx4 v[76:77], v[68:71], off offset:256 nt
	global_store_dwordx4 v[64:65], v[60:63], off nt
	global_store_dwordx4 v[44:45], v[40:43], off nt
	global_store_dwordx4 v[28:29], v[24:27], off nt
	global_store_dwordx4 v[12:13], v[8:11], off nt
	global_store_dwordx4 v[12:13], v[4:7], off offset:256 nt
	s_cbranch_vccnz .LBB0_285
	s_andn2_b64 vcc, exec, s[0:1]
	s_cbranch_vccnz .LBB0_284
	s_barrier
	s_branch .LBB0_284

; __device__ __forceinline__ unsigned cvt_pk_bf16(float lo, float hi) { const f32x2 v = {lo, hi}; return __builtin_bit_cast(unsigned, __builtin_convertvector(v, bf16x2_t)); }
; __device__ __forceinline__ float sigm(float x) { return 1.0f / (1.0f + __expf(-x)); }
;     __device__ __forceinline__ void operator()(AccRef acc, const Unit& u, int wr, int wc, int fr, int fq) const {
;     ...
;             if (pn < 13) { base = PR; ldc = RP; colt = pn * 256; } else { ldc = D; sg = pn >= 17; colt = ((pn - 13) & 3) * 256; base = sg ? SG0 : PL; }
; #pragma unroll
;             for (int ai = 0; ai < 2; ++ai)
; #pragma unroll
;                 for (int m = 0; m < 4; ++m) { bf16_t* rowp = base + (size_t)EPI_ROWS(ai, m) * ldc + colt + cw;
; #pragma unroll
;                     for (int bj = 0; bj < 2; ++bj) { f32x4 v0 = acc[ai][bj][m][0], v1 = acc[ai][bj][m][1];
;                         if (sg) { v0 = (f32x4){sigm(v0[0]), sigm(v0[1]), sigm(v0[2]), sigm(v0[3])}; v1 = (f32x4){sigm(v1[0]), sigm(v1[1]), sigm(v1[2]), sigm(v1[3])}; }
;                         u32x4 w; w.x = cvt_pk_bf16(v0[0], v0[1]); w.y = cvt_pk_bf16(v0[2], v0[3]); w.z = cvt_pk_bf16(v1[0], v1[1]); w.w = cvt_pk_bf16(v1[2], v1[3]);
;                         if (EPI_ROWS(ai, m) < MT) *(u32x4*)(rowp + bj * HALF) = w; } }
.LBB0_531:
	s_add_u32 s0, s34, s54
	s_addc_u32 s25, s35, s55
	s_ashr_i32 s5, s4, 31
	s_lshl_b64 s[4:5], s[4:5], 1
	s_add_u32 s4, s0, s4
	v_lshl_add_u32 v144, s46, 8, v157
	s_addc_u32 s5, s25, s5
	v_mov_b32_e32 v151, v145
	v_lshl_add_u64 v[152:153], s[4:5], 0, v[150:151]
	v_mad_i64_i32 v[154:155], s[4:5], s52, v144, 0
	v_lshl_add_u64 v[154:155], v[154:155], 1, v[152:153]
	v_cmp_gt_i32_e64 s[4:5], s91, v144
	s_and_saveexec_b64 s[54:55], s[4:5]
	s_cbranch_execz .LBB0_533
	v_cvt_pk_bf16_f32 v128, v128, v129
	v_cvt_pk_bf16_f32 v129, v130, v131
	v_cvt_pk_bf16_f32 v130, v132, v133
	v_cvt_pk_bf16_f32 v131, v134, v135
	global_store_dwordx4 v[154:155], v[128:131], off nt

; __device__ __forceinline__ unsigned cvt_pk_bf16(float lo, float hi) { const f32x2 v = {lo, hi}; return __builtin_bit_cast(unsigned, __builtin_convertvector(v, bf16x2_t)); }
; __device__ __forceinline__ float sigm(float x) { return 1.0f / (1.0f + __expf(-x)); }
;     __device__ __forceinline__ void operator()(AccRef acc, const Unit& u, int wr, int wc, int fr, int fq) const {
;     ...
;                 for (int m = 0; m < 4; ++m) { bf16_t* rowp = base + (size_t)EPI_ROWS(ai, m) * ldc + colt + cw;
; #pragma unroll
;                     for (int bj = 0; bj < 2; ++bj) { f32x4 v0 = acc[ai][bj][m][0], v1 = acc[ai][bj][m][1];
;                         if (sg) { v0 = (f32x4){sigm(v0[0]), sigm(v0[1]), sigm(v0[2]), sigm(v0[3])}; v1 = (f32x4){sigm(v1[0]), sigm(v1[1]), sigm(v1[2]), sigm(v1[3])}; }
;                         u32x4 w; w.x = cvt_pk_bf16(v0[0], v0[1]); w.y = cvt_pk_bf16(v0[2], v0[3]); w.z = cvt_pk_bf16(v1[0], v1[1]); w.w = cvt_pk_bf16(v1[2], v1[3]);
;                         if (EPI_ROWS(ai, m) < MT) *(u32x4*)(rowp + bj * HALF) = w; } }
.LBB0_535:
	s_and_saveexec_b64 s[54:55], s[4:5]
	s_cbranch_execz .LBB0_537
	v_cvt_pk_bf16_f32 v128, v128, v129
	v_cvt_pk_bf16_f32 v129, v130, v131
	v_cvt_pk_bf16_f32 v130, v132, v133
	v_cvt_pk_bf16_f32 v131, v134, v135
	global_store_dwordx4 v[154:155], v[128:131], off offset:256 nt

; __device__ __forceinline__ unsigned cvt_pk_bf16(float lo, float hi) { const f32x2 v = {lo, hi}; return __builtin_bit_cast(unsigned, __builtin_convertvector(v, bf16x2_t)); }
; __device__ __forceinline__ float sigm(float x) { return 1.0f / (1.0f + __expf(-x)); }
;     __device__ __forceinline__ void operator()(AccRef acc, const Unit& u, int wr, int wc, int fr, int fq) const {
;     ...
;                 for (int m = 0; m < 4; ++m) { bf16_t* rowp = base + (size_t)EPI_ROWS(ai, m) * ldc + colt + cw;
; #pragma unroll
;                     for (int bj = 0; bj < 2; ++bj) { f32x4 v0 = acc[ai][bj][m][0], v1 = acc[ai][bj][m][1];
;                         if (sg) { v0 = (f32x4){sigm(v0[0]), sigm(v0[1]), sigm(v0[2]), sigm(v0[3])}; v1 = (f32x4){sigm(v1[0]), sigm(v1[1]), sigm(v1[2]), sigm(v1[3])}; }
;                         u32x4 w; w.x = cvt_pk_bf16(v0[0], v0[1]); w.y = cvt_pk_bf16(v0[2], v0[3]); w.z = cvt_pk_bf16(v1[0], v1[1]); w.w = cvt_pk_bf16(v1[2], v1[3]);
;                         if (EPI_ROWS(ai, m) < MT) *(u32x4*)(rowp + bj * HALF) = w; } }
.LBB0_539:
	v_or_b32_e32 v151, 16, v144
	v_mad_i64_i32 v[154:155], s[4:5], s52, v151, 0
	v_lshl_add_u64 v[154:155], v[154:155], 1, v[152:153]
	v_cmp_gt_i32_e64 s[4:5], s91, v151
	s_and_saveexec_b64 s[54:55], s[4:5]
	s_cbranch_execz .LBB0_541
	v_cvt_pk_bf16_f32 v128, v128, v129
	v_cvt_pk_bf16_f32 v129, v130, v131
	v_cvt_pk_bf16_f32 v130, v132, v133
	v_cvt_pk_bf16_f32 v131, v134, v135
	global_store_dwordx4 v[154:155], v[128:131], off nt

; __device__ __forceinline__ unsigned cvt_pk_bf16(float lo, float hi) { const f32x2 v = {lo, hi}; return __builtin_bit_cast(unsigned, __builtin_convertvector(v, bf16x2_t)); }
; __device__ __forceinline__ float sigm(float x) { return 1.0f / (1.0f + __expf(-x)); }
;     __device__ __forceinline__ void operator()(AccRef acc, const Unit& u, int wr, int wc, int fr, int fq) const {
;     ...
;                 for (int m = 0; m < 4; ++m) { bf16_t* rowp = base + (size_t)EPI_ROWS(ai, m) * ldc + colt + cw;
; #pragma unroll
;                     for (int bj = 0; bj < 2; ++bj) { f32x4 v0 = acc[ai][bj][m][0], v1 = acc[ai][bj][m][1];
;                         if (sg) { v0 = (f32x4){sigm(v0[0]), sigm(v0[1]), sigm(v0[2]), sigm(v0[3])}; v1 = (f32x4){sigm(v1[0]), sigm(v1[1]), sigm(v1[2]), sigm(v1[3])}; }
;                         u32x4 w; w.x = cvt_pk_bf16(v0[0], v0[1]); w.y = cvt_pk_bf16(v0[2], v0[3]); w.z = cvt_pk_bf16(v1[0], v1[1]); w.w = cvt_pk_bf16(v1[2], v1[3]);
;                         if (EPI_ROWS(ai, m) < MT) *(u32x4*)(rowp + bj * HALF) = w; } }
.LBB0_547:
	v_or_b32_e32 v151, 32, v144
	v_mad_i64_i32 v[154:155], s[4:5], s52, v151, 0
	v_lshl_add_u64 v[154:155], v[154:155], 1, v[152:153]
	v_cmp_gt_i32_e64 s[4:5], s91, v151
	s_and_saveexec_b64 s[54:55], s[4:5]
	s_cbranch_execz .LBB0_549
	v_cvt_pk_bf16_f32 v128, v128, v129
	v_cvt_pk_bf16_f32 v129, v130, v131
	v_cvt_pk_bf16_f32 v130, v132, v133
	v_cvt_pk_bf16_f32 v131, v134, v135
	global_store_dwordx4 v[154:155], v[128:131], off nt

; __device__ __forceinline__ unsigned cvt_pk_bf16(float lo, float hi) { const f32x2 v = {lo, hi}; return __builtin_bit_cast(unsigned, __builtin_convertvector(v, bf16x2_t)); }
; __device__ __forceinline__ float sigm(float x) { return 1.0f / (1.0f + __expf(-x)); }
;     __device__ __forceinline__ void operator()(AccRef acc, const Unit& u, int wr, int wc, int fr, int fq) const {
;     ...
;                 for (int m = 0; m < 4; ++m) { bf16_t* rowp = base + (size_t)EPI_ROWS(ai, m) * ldc + colt + cw;
; #pragma unroll
;                     for (int bj = 0; bj < 2; ++bj) { f32x4 v0 = acc[ai][bj][m][0], v1 = acc[ai][bj][m][1];
;                         if (sg) { v0 = (f32x4){sigm(v0[0]), sigm(v0[1]), sigm(v0[2]), sigm(v0[3])}; v1 = (f32x4){sigm(v1[0]), sigm(v1[1]), sigm(v1[2]), sigm(v1[3])}; }
;                         u32x4 w; w.x = cvt_pk_bf16(v0[0], v0[1]); w.y = cvt_pk_bf16(v0[2], v0[3]); w.z = cvt_pk_bf16(v1[0], v1[1]); w.w = cvt_pk_bf16(v1[2], v1[3]);
;                         if (EPI_ROWS(ai, m) < MT) *(u32x4*)(rowp + bj * HALF) = w; } }
.LBB0_555:
	v_or_b32_e32 v151, 48, v144
	v_mad_i64_i32 v[154:155], s[4:5], s52, v151, 0
	v_lshl_add_u64 v[154:155], v[154:155], 1, v[152:153]
	v_cmp_gt_i32_e64 s[4:5], s91, v151
	s_and_saveexec_b64 s[54:55], s[4:5]
	s_cbranch_execz .LBB0_557
	v_cvt_pk_bf16_f32 v128, v128, v129
	v_cvt_pk_bf16_f32 v129, v130, v131
	v_cvt_pk_bf16_f32 v130, v132, v133
	v_cvt_pk_bf16_f32 v131, v134, v135
	global_store_dwordx4 v[154:155], v[128:131], off nt

; __device__ __forceinline__ unsigned cvt_pk_bf16(float lo, float hi) { const f32x2 v = {lo, hi}; return __builtin_bit_cast(unsigned, __builtin_convertvector(v, bf16x2_t)); }
; __device__ __forceinline__ float sigm(float x) { return 1.0f / (1.0f + __expf(-x)); }
;     __device__ __forceinline__ void operator()(AccRef acc, const Unit& u, int wr, int wc, int fr, int fq) const {
;     ...
;                 for (int m = 0; m < 4; ++m) { bf16_t* rowp = base + (size_t)EPI_ROWS(ai, m) * ldc + colt + cw;
; #pragma unroll
;                     for (int bj = 0; bj < 2; ++bj) { f32x4 v0 = acc[ai][bj][m][0], v1 = acc[ai][bj][m][1];
;                         if (sg) { v0 = (f32x4){sigm(v0[0]), sigm(v0[1]), sigm(v0[2]), sigm(v0[3])}; v1 = (f32x4){sigm(v1[0]), sigm(v1[1]), sigm(v1[2]), sigm(v1[3])}; }
;                         u32x4 w; w.x = cvt_pk_bf16(v0[0], v0[1]); w.y = cvt_pk_bf16(v0[2], v0[3]); w.z = cvt_pk_bf16(v1[0], v1[1]); w.w = cvt_pk_bf16(v1[2], v1[3]);
;                         if (EPI_ROWS(ai, m) < MT) *(u32x4*)(rowp + bj * HALF) = w; } }
.LBB0_563:
	v_add_u32_e32 v151, 0x80, v144
	v_mad_i64_i32 v[154:155], s[4:5], s52, v151, 0
	v_lshl_add_u64 v[154:155], v[154:155], 1, v[152:153]
	v_cmp_gt_i32_e64 s[4:5], s91, v151
	s_and_saveexec_b64 s[54:55], s[4:5]
	s_cbranch_execz .LBB0_565
	v_cvt_pk_bf16_f32 v128, v128, v129
	v_cvt_pk_bf16_f32 v129, v130, v131
	v_cvt_pk_bf16_f32 v130, v132, v133
	v_cvt_pk_bf16_f32 v131, v134, v135
	global_store_dwordx4 v[154:155], v[128:131], off nt

; __device__ __forceinline__ unsigned cvt_pk_bf16(float lo, float hi) { const f32x2 v = {lo, hi}; return __builtin_bit_cast(unsigned, __builtin_convertvector(v, bf16x2_t)); }
; __device__ __forceinline__ float sigm(float x) { return 1.0f / (1.0f + __expf(-x)); }
;     __device__ __forceinline__ void operator()(AccRef acc, const Unit& u, int wr, int wc, int fr, int fq) const {
;     ...
;                 for (int m = 0; m < 4; ++m) { bf16_t* rowp = base + (size_t)EPI_ROWS(ai, m) * ldc + colt + cw;
; #pragma unroll
;                     for (int bj = 0; bj < 2; ++bj) { f32x4 v0 = acc[ai][bj][m][0], v1 = acc[ai][bj][m][1];
;                         if (sg) { v0 = (f32x4){sigm(v0[0]), sigm(v0[1]), sigm(v0[2]), sigm(v0[3])}; v1 = (f32x4){sigm(v1[0]), sigm(v1[1]), sigm(v1[2]), sigm(v1[3])}; }
;                         u32x4 w; w.x = cvt_pk_bf16(v0[0], v0[1]); w.y = cvt_pk_bf16(v0[2], v0[3]); w.z = cvt_pk_bf16(v1[0], v1[1]); w.w = cvt_pk_bf16(v1[2], v1[3]);
;                         if (EPI_ROWS(ai, m) < MT) *(u32x4*)(rowp + bj * HALF) = w; } }
.LBB0_571:
	v_add_u32_e32 v151, 0x90, v144
	v_mad_i64_i32 v[154:155], s[4:5], s52, v151, 0
	v_lshl_add_u64 v[154:155], v[154:155], 1, v[152:153]
	v_cmp_gt_i32_e64 s[4:5], s91, v151
	s_and_saveexec_b64 s[54:55], s[4:5]
	s_cbranch_execz .LBB0_573
	v_cvt_pk_bf16_f32 v128, v128, v129
	v_cvt_pk_bf16_f32 v129, v130, v131
	v_cvt_pk_bf16_f32 v130, v132, v133
	v_cvt_pk_bf16_f32 v131, v134, v135
	global_store_dwordx4 v[154:155], v[128:131], off nt

; __device__ __forceinline__ unsigned cvt_pk_bf16(float lo, float hi) { const f32x2 v = {lo, hi}; return __builtin_bit_cast(unsigned, __builtin_convertvector(v, bf16x2_t)); }
; __device__ __forceinline__ float sigm(float x) { return 1.0f / (1.0f + __expf(-x)); }
;     __device__ __forceinline__ void operator()(AccRef acc, const Unit& u, int wr, int wc, int fr, int fq) const {
;     ...
;                 for (int m = 0; m < 4; ++m) { bf16_t* rowp = base + (size_t)EPI_ROWS(ai, m) * ldc + colt + cw;
; #pragma unroll
;                     for (int bj = 0; bj < 2; ++bj) { f32x4 v0 = acc[ai][bj][m][0], v1 = acc[ai][bj][m][1];
;                         if (sg) { v0 = (f32x4){sigm(v0[0]), sigm(v0[1]), sigm(v0[2]), sigm(v0[3])}; v1 = (f32x4){sigm(v1[0]), sigm(v1[1]), sigm(v1[2]), sigm(v1[3])}; }
;                         u32x4 w; w.x = cvt_pk_bf16(v0[0], v0[1]); w.y = cvt_pk_bf16(v0[2], v0[3]); w.z = cvt_pk_bf16(v1[0], v1[1]); w.w = cvt_pk_bf16(v1[2], v1[3]);
;                         if (EPI_ROWS(ai, m) < MT) *(u32x4*)(rowp + bj * HALF) = w; } }
.LBB0_579:
	v_add_u32_e32 v151, 0xa0, v144
	v_mad_i64_i32 v[154:155], s[4:5], s52, v151, 0
	v_lshl_add_u64 v[154:155], v[154:155], 1, v[152:153]
	v_cmp_gt_i32_e64 s[4:5], s91, v151
	s_and_saveexec_b64 s[54:55], s[4:5]
	s_cbranch_execz .LBB0_581
	v_cvt_pk_bf16_f32 v128, v128, v129
	v_cvt_pk_bf16_f32 v129, v130, v131
	v_cvt_pk_bf16_f32 v130, v132, v133
	v_cvt_pk_bf16_f32 v131, v134, v135
	global_store_dwordx4 v[154:155], v[128:131], off nt

; __device__ __forceinline__ unsigned cvt_pk_bf16(float lo, float hi) { const f32x2 v = {lo, hi}; return __builtin_bit_cast(unsigned, __builtin_convertvector(v, bf16x2_t)); }
; __device__ __forceinline__ float sigm(float x) { return 1.0f / (1.0f + __expf(-x)); }
;     __device__ __forceinline__ void operator()(AccRef acc, const Unit& u, int wr, int wc, int fr, int fq) const {
;     ...
;                 for (int m = 0; m < 4; ++m) { bf16_t* rowp = base + (size_t)EPI_ROWS(ai, m) * ldc + colt + cw;
; #pragma unroll
;                     for (int bj = 0; bj < 2; ++bj) { f32x4 v0 = acc[ai][bj][m][0], v1 = acc[ai][bj][m][1];
;                         if (sg) { v0 = (f32x4){sigm(v0[0]), sigm(v0[1]), sigm(v0[2]), sigm(v0[3])}; v1 = (f32x4){sigm(v1[0]), sigm(v1[1]), sigm(v1[2]), sigm(v1[3])}; }
;                         u32x4 w; w.x = cvt_pk_bf16(v0[0], v0[1]); w.y = cvt_pk_bf16(v0[2], v0[3]); w.z = cvt_pk_bf16(v1[0], v1[1]); w.w = cvt_pk_bf16(v1[2], v1[3]);
;                         if (EPI_ROWS(ai, m) < MT) *(u32x4*)(rowp + bj * HALF) = w; } }
.LBB0_587:
	v_add_u32_e32 v144, 0xb0, v144
	v_mad_i64_i32 v[154:155], s[4:5], s52, v144, 0
	v_lshl_add_u64 v[152:153], v[154:155], 1, v[152:153]
	v_cmp_gt_i32_e64 s[4:5], s91, v144
	s_and_saveexec_b64 s[52:53], s[4:5]
	s_cbranch_execz .LBB0_589
	v_cvt_pk_bf16_f32 v128, v128, v129
	v_cvt_pk_bf16_f32 v129, v130, v131
	v_cvt_pk_bf16_f32 v130, v132, v133
	v_cvt_pk_bf16_f32 v131, v134, v135
	global_store_dwordx4 v[152:153], v[128:131], off nt

; __device__ __forceinline__ unsigned cvt_pk_bf16(float lo, float hi) { const f32x2 v = {lo, hi}; return __builtin_bit_cast(unsigned, __builtin_convertvector(v, bf16x2_t)); }
; __device__ __forceinline__ float sigm(float x) { return 1.0f / (1.0f + __expf(-x)); }
;     __device__ __forceinline__ void operator()(AccRef acc, const Unit& u, int wr, int wc, int fr, int fq) const {
;     ...
;                 for (int m = 0; m < 4; ++m) { bf16_t* rowp = base + (size_t)EPI_ROWS(ai, m) * ldc + colt + cw;
; #pragma unroll
;                     for (int bj = 0; bj < 2; ++bj) { f32x4 v0 = acc[ai][bj][m][0], v1 = acc[ai][bj][m][1];
;                         if (sg) { v0 = (f32x4){sigm(v0[0]), sigm(v0[1]), sigm(v0[2]), sigm(v0[3])}; v1 = (f32x4){sigm(v1[0]), sigm(v1[1]), sigm(v1[2]), sigm(v1[3])}; }
;                         u32x4 w; w.x = cvt_pk_bf16(v0[0], v0[1]); w.y = cvt_pk_bf16(v0[2], v0[3]); w.z = cvt_pk_bf16(v1[0], v1[1]); w.w = cvt_pk_bf16(v1[2], v1[3]);
;                         if (EPI_ROWS(ai, m) < MT) *(u32x4*)(rowp + bj * HALF) = w; } }
.LBB0_591:
	s_and_saveexec_b64 s[2:3], s[4:5]
	s_cbranch_execz .LBB0_593
	v_cvt_pk_bf16_f32 v128, v128, v129
	v_cvt_pk_bf16_f32 v129, v130, v131
	v_cvt_pk_bf16_f32 v130, v132, v133
	v_cvt_pk_bf16_f32 v131, v134, v135
	global_store_dwordx4 v[152:153], v[128:131], off offset:256 nt

; __device__ __forceinline__ unsigned cvt_pk_bf16(float lo, float hi) { const f32x2 v = {lo, hi}; return __builtin_bit_cast(unsigned, __builtin_convertvector(v, bf16x2_t)); }
; __device__ __forceinline__ float sigm(float x) { return 1.0f / (1.0f + __expf(-x)); }
; __device__ __forceinline__ float gelu_t(float x) { float u = 0.7978845608028654f * (x + 0.044715f * x * x * x); return 0.5f * x * (1.0f + tanh_(u)); }
;     __device__ __forceinline__ void operator()(AccRef acc, const Unit& u, int wr, int wc, int fr, int fq) const {
;     ...
;             const int col0 = (pn - 17) * 128 + cw;
; #pragma unroll
;             for (int ai = 0; ai < 2; ++ai)
; #pragma unroll
;                 for (int m = 0; m < 4; ++m) {
;                     const f32x4 g0 = acc[ai][0][m][0], g1 = acc[ai][0][m][1], s0 = acc[ai][1][m][0], s1 = acc[ai][1][m][1];
;                     u32x4 w;
;                     w.x = cvt_pk_bf16(gelu_t(g0[0]) * sigm(s0[0]), gelu_t(g0[1]) * sigm(s0[1])); w.y = cvt_pk_bf16(gelu_t(g0[2]) * sigm(s0[2]), gelu_t(g0[3]) * sigm(s0[3]));
;                     w.z = cvt_pk_bf16(gelu_t(g1[0]) * sigm(s1[0]), gelu_t(g1[1]) * sigm(s1[1])); w.w = cvt_pk_bf16(gelu_t(g1[2]) * sigm(s1[2]), gelu_t(g1[3]) * sigm(s1[3]));
;                     if (EPI_ROWS(ai, m) < MT) *(u32x4*)(GG + (size_t)EPI_ROWS(ai, m) * D + col0) = w;
.LBB0_594:
	v_lshl_add_u32 v128, s46, 8, v157
	v_lshl_add_u32 v144, s44, 7, v159
	v_cmp_gt_i32_e32 vcc, s91, v128
	s_and_saveexec_b64 s[2:3], vcc
	s_cbranch_execz .LBB0_596
	v_mul_f32_e32 v130, 0x3d372713, v124
	v_mul_f32_e32 v130, v124, v130
	v_fma_f32 v130, v124, v130, v124
	v_mul_f32_e32 v130, 0x3f4c422a, v130
	v_add_f32_e32 v130, v130, v130
	v_mul_f32_e32 v130, 0x3fb8aa3b, v130
	v_exp_f32_e32 v132, v130
	v_mul_f32_e32 v130, 0x3d372713, v125
	v_mul_f32_e32 v130, v125, v130
	v_fma_f32 v130, v125, v130, v125
	v_mul_f32_e32 v130, 0x3f4c422a, v130
	v_add_f32_e32 v130, v130, v130
	v_mul_f32_e32 v130, 0x3fb8aa3b, v130
	v_exp_f32_e32 v133, v130
	v_ashrrev_i32_e32 v129, 31, v128
	v_lshlrev_b64 v[130:131], 11, v[128:129]
	v_mul_f32_e32 v120, 0xbfb8aa3b, v120
	v_pk_add_f32 v[132:133], v[132:133], 1.0 op_sel_hi:[1,0]
	v_mul_f32_e32 v121, 0xbfb8aa3b, v121
	v_exp_f32_e32 v120, v120
	v_exp_f32_e32 v121, v121
	v_pk_mul_f32 v[124:125], v[124:125], 0.5 op_sel_hi:[1,0]
	v_rcp_f32_e32 v133, v133
	s_nop 0
	v_mul_f32_e32 v133, 2.0, v133
	v_pk_add_f32 v[120:121], v[120:121], 1.0 op_sel_hi:[1,0]
	v_rcp_f32_e32 v132, v132
	s_nop 0
	v_mul_f32_e32 v132, 2.0, v132
	v_pk_add_f32 v[132:133], v[132:133], 1.0 op_sel_hi:[1,0] neg_lo:[1,0] neg_hi:[1,0]
	v_mul_f32_e32 v123, 0xbfb8aa3b, v123
	v_pk_add_f32 v[132:133], v[132:133], 1.0 op_sel_hi:[1,0]
	v_exp_f32_e32 v123, v123
	v_pk_mul_f32 v[124:125], v[124:125], v[132:133]
	v_rcp_f32_e32 v121, v121
	v_mul_f32_e32 v112, 0xbfb8aa3b, v112
	v_rcp_f32_e32 v120, v120
	s_nop 0
	v_pk_mul_f32 v[120:121], v[124:125], v[120:121]
	v_mul_f32_e32 v124, 0x3d372713, v126
	v_mul_f32_e32 v125, 0x3d372713, v127
	v_mul_f32_e32 v124, v126, v124
	v_mul_f32_e32 v125, v127, v125
	v_fma_f32 v124, v126, v124, v126
	v_fma_f32 v125, v127, v125, v127
	v_mul_f32_e32 v124, 0x3f4c422a, v124
	v_mul_f32_e32 v125, 0x3f4c422a, v125
	v_add_f32_e32 v124, v124, v124
	v_add_f32_e32 v125, v125, v125
	v_mul_f32_e32 v124, 0x3fb8aa3b, v124
	v_mul_f32_e32 v125, 0x3fb8aa3b, v125
	v_exp_f32_e32 v124, v124
	v_exp_f32_e32 v125, v125
	v_cvt_pk_bf16_f32 v120, v120, v121
	v_mul_f32_e32 v121, 0xbfb8aa3b, v122
	v_exp_f32_e32 v122, v121
	v_pk_add_f32 v[124:125], v[124:125], 1.0 op_sel_hi:[1,0]
	v_pk_mul_f32 v[126:127], v[126:127], 0.5 op_sel_hi:[1,0]
	v_pk_add_f32 v[122:123], v[122:123], 1.0 op_sel_hi:[1,0]
	v_mul_f32_e32 v113, 0xbfb8aa3b, v113
	v_exp_f32_e32 v112, v112
	v_rcp_f32_e32 v125, v125
	s_nop 0
	v_mul_f32_e32 v125, 2.0, v125
	v_exp_f32_e32 v113, v113
	v_rcp_f32_e32 v124, v124
	s_nop 0
	v_mul_f32_e32 v124, 2.0, v124
	v_pk_add_f32 v[124:125], v[124:125], 1.0 op_sel_hi:[1,0] neg_lo:[1,0] neg_hi:[1,0]
	v_pk_add_f32 v[112:113], v[112:113], 1.0 op_sel_hi:[1,0]
	v_pk_add_f32 v[124:125], v[124:125], 1.0 op_sel_hi:[1,0]
	s_nop 0
	v_pk_mul_f32 v[124:125], v[126:127], v[124:125]
	v_rcp_f32_e32 v123, v123
	v_rcp_f32_e32 v122, v122
	v_mul_f32_e32 v121, 0x3d372713, v116
	v_mul_f32_e32 v121, v116, v121
	v_fma_f32 v121, v116, v121, v116
	v_mul_f32_e32 v121, 0x3f4c422a, v121
	v_add_f32_e32 v121, v121, v121
	v_mul_f32_e32 v121, 0x3fb8aa3b, v121
	v_pk_mul_f32 v[122:123], v[124:125], v[122:123]
	v_exp_f32_e32 v124, v121
	v_mul_f32_e32 v121, 0x3d372713, v117
	v_mul_f32_e32 v121, v117, v121
	v_fma_f32 v121, v117, v121, v117
	v_mul_f32_e32 v121, 0x3f4c422a, v121
	v_add_f32_e32 v121, v121, v121
	v_mul_f32_e32 v121, 0x3fb8aa3b, v121
	v_exp_f32_e32 v125, v121
	v_cvt_pk_bf16_f32 v121, v122, v123
	v_pk_mul_f32 v[116:117], v[116:117], 0.5 op_sel_hi:[1,0]
	v_pk_add_f32 v[122:123], v[124:125], 1.0 op_sel_hi:[1,0]
	s_nop 0
	s_nop 0
	v_rcp_f32_e32 v123, v123
	s_nop 0
	v_mul_f32_e32 v123, 2.0, v123
	v_rcp_f32_e32 v122, v122
	s_nop 0
	v_mul_f32_e32 v122, 2.0, v122
	v_pk_add_f32 v[122:123], v[122:123], 1.0 op_sel_hi:[1,0] neg_lo:[1,0] neg_hi:[1,0]
	s_nop 0
	v_pk_add_f32 v[122:123], v[122:123], 1.0 op_sel_hi:[1,0]
	s_nop 0
	v_pk_mul_f32 v[116:117], v[116:117], v[122:123]
	v_rcp_f32_e32 v113, v113
	v_rcp_f32_e32 v112, v112
	s_nop 0
	v_pk_mul_f32 v[112:113], v[116:117], v[112:113]
	v_mul_f32_e32 v116, 0x3d372713, v118
	v_mul_f32_e32 v117, 0x3d372713, v119
	v_mul_f32_e32 v116, v118, v116
	v_mul_f32_e32 v117, v119, v117
	v_fma_f32 v116, v118, v116, v118
	v_fma_f32 v117, v119, v117, v119
	v_mul_f32_e32 v116, 0x3f4c422a, v116
	v_mul_f32_e32 v117, 0x3f4c422a, v117
	v_add_f32_e32 v116, v116, v116
	v_add_f32_e32 v117, v117, v117
	v_mul_f32_e32 v116, 0x3fb8aa3b, v116
	v_mul_f32_e32 v117, 0x3fb8aa3b, v117
	v_exp_f32_e32 v116, v116
	v_exp_f32_e32 v117, v117
	v_cvt_pk_bf16_f32 v122, v112, v113
	v_mul_f32_e32 v112, 0xbfb8aa3b, v114
	v_mul_f32_e32 v113, 0xbfb8aa3b, v115
	v_pk_add_f32 v[116:117], v[116:117], 1.0 op_sel_hi:[1,0]
	v_pk_mul_f32 v[114:115], v[118:119], 0.5 op_sel_hi:[1,0]
	v_exp_f32_e32 v112, v112
	v_exp_f32_e32 v113, v113
	v_rcp_f32_e32 v117, v117
	s_nop 0
	v_mul_f32_e32 v117, 2.0, v117
	v_pk_add_f32 v[112:113], v[112:113], 1.0 op_sel_hi:[1,0]
	v_rcp_f32_e32 v116, v116
	s_nop 0
	v_mul_f32_e32 v116, 2.0, v116
	v_pk_add_f32 v[116:117], v[116:117], 1.0 op_sel_hi:[1,0] neg_lo:[1,0] neg_hi:[1,0]
	s_nop 0
	v_pk_add_f32 v[116:117], v[116:117], 1.0 op_sel_hi:[1,0]
	s_nop 0
	v_pk_mul_f32 v[114:115], v[114:115], v[116:117]
	v_rcp_f32_e32 v113, v113
	v_rcp_f32_e32 v112, v112
	s_nop 0
	v_pk_mul_f32 v[112:113], v[114:115], v[112:113]
	s_nop 0
	v_cvt_pk_bf16_f32 v123, v112, v113
	v_lshl_add_u64 v[112:113], s[8:9], 0, v[130:131]
	v_lshl_add_u64 v[112:113], v[144:145], 1, v[112:113]
	global_store_dwordx4 v[112:113], v[120:123], off nt
; __device__ __forceinline__ unsigned cvt_pk_bf16(float lo, float hi) { const f32x2 v = {lo, hi}; return __builtin_bit_cast(unsigned, __builtin_convertvector(v, bf16x2_t)); }
; __device__ __forceinline__ float sigm(float x) { return 1.0f / (1.0f + __expf(-x)); }
; __device__ __forceinline__ float gelu_t(float x) { float u = 0.7978845608028654f * (x + 0.044715f * x * x * x); return 0.5f * x * (1.0f + tanh_(u)); }
;     __device__ __forceinline__ void operator()(AccRef acc, const Unit& u, int wr, int wc, int fr, int fq) const {
;     ...
;             const int col0 = (pn - 17) * 128 + cw;
; #pragma unroll
;             for (int ai = 0; ai < 2; ++ai)
; #pragma unroll
;                 for (int m = 0; m < 4; ++m) {
;                     const f32x4 g0 = acc[ai][0][m][0], g1 = acc[ai][0][m][1], s0 = acc[ai][1][m][0], s1 = acc[ai][1][m][1];
;                     u32x4 w;
;                     w.x = cvt_pk_bf16(gelu_t(g0[0]) * sigm(s0[0]), gelu_t(g0[1]) * sigm(s0[1])); w.y = cvt_pk_bf16(gelu_t(g0[2]) * sigm(s0[2]), gelu_t(g0[3]) * sigm(s0[3]));
;                     w.z = cvt_pk_bf16(gelu_t(g1[0]) * sigm(s1[0]), gelu_t(g1[1]) * sigm(s1[1])); w.w = cvt_pk_bf16(gelu_t(g1[2]) * sigm(s1[2]), gelu_t(g1[3]) * sigm(s1[3]));
;                     if (EPI_ROWS(ai, m) < MT) *(u32x4*)(GG + (size_t)EPI_ROWS(ai, m) * D + col0) = w;
.LBB0_596:
	s_or_b64 exec, exec, s[2:3]
	v_or_b32_e32 v112, 16, v128
	v_cmp_gt_i32_e32 vcc, s91, v112
	s_and_saveexec_b64 s[2:3], vcc
	s_cbranch_execz .LBB0_598
	v_mul_f32_e32 v114, 0x3d372713, v108
	v_mul_f32_e32 v115, 0x3d372713, v109
	v_mul_f32_e32 v114, v108, v114
	v_mul_f32_e32 v115, v109, v115
	v_fma_f32 v114, v108, v114, v108
	v_fma_f32 v115, v109, v115, v109
	v_mul_f32_e32 v114, 0x3f4c422a, v114
	v_mul_f32_e32 v115, 0x3f4c422a, v115
	v_add_f32_e32 v114, v114, v114
	v_add_f32_e32 v115, v115, v115
	v_mul_f32_e32 v114, 0x3fb8aa3b, v114
	v_mul_f32_e32 v115, 0x3fb8aa3b, v115
	v_exp_f32_e32 v114, v114
	v_exp_f32_e32 v115, v115
	v_mul_f32_e32 v104, 0xbfb8aa3b, v104
	v_mul_f32_e32 v105, 0xbfb8aa3b, v105
	v_exp_f32_e32 v104, v104
	v_pk_add_f32 v[114:115], v[114:115], 1.0 op_sel_hi:[1,0]
	v_exp_f32_e32 v105, v105
	s_nop 0
	v_pk_add_f32 v[104:105], v[104:105], 1.0 op_sel_hi:[1,0]
	v_pk_mul_f32 v[108:109], v[108:109], 0.5 op_sel_hi:[1,0]
	v_mul_f32_e32 v107, 0xbfb8aa3b, v107
	v_rcp_f32_e32 v115, v115
	s_nop 0
	v_mul_f32_e32 v115, 2.0, v115
	v_exp_f32_e32 v107, v107
	v_rcp_f32_e32 v114, v114
	s_nop 0
	v_mul_f32_e32 v114, 2.0, v114
	v_pk_add_f32 v[114:115], v[114:115], 1.0 op_sel_hi:[1,0] neg_lo:[1,0] neg_hi:[1,0]
	v_mul_f32_e32 v96, 0xbfb8aa3b, v96
	v_pk_add_f32 v[114:115], v[114:115], 1.0 op_sel_hi:[1,0]
	v_mul_f32_e32 v97, 0xbfb8aa3b, v97
	v_pk_mul_f32 v[108:109], v[108:109], v[114:115]
	v_rcp_f32_e32 v105, v105
	v_exp_f32_e32 v96, v96
	v_rcp_f32_e32 v104, v104
	s_nop 0
	v_pk_mul_f32 v[104:105], v[108:109], v[104:105]
	v_mul_f32_e32 v108, 0x3d372713, v110
	v_mul_f32_e32 v109, 0x3d372713, v111
	v_mul_f32_e32 v108, v110, v108
	v_mul_f32_e32 v109, v111, v109
	v_fma_f32 v108, v110, v108, v110
	v_fma_f32 v109, v111, v109, v111
	v_mul_f32_e32 v108, 0x3f4c422a, v108
	v_mul_f32_e32 v109, 0x3f4c422a, v109
	v_add_f32_e32 v108, v108, v108
	v_add_f32_e32 v109, v109, v109
	v_mul_f32_e32 v108, 0x3fb8aa3b, v108
	v_mul_f32_e32 v109, 0x3fb8aa3b, v109
	v_exp_f32_e32 v108, v108
	v_exp_f32_e32 v109, v109
	v_cvt_pk_bf16_f32 v104, v104, v105
	v_mul_f32_e32 v105, 0xbfb8aa3b, v106
	v_exp_f32_e32 v106, v105
	v_pk_add_f32 v[108:109], v[108:109], 1.0 op_sel_hi:[1,0]
	v_pk_mul_f32 v[110:111], v[110:111], 0.5 op_sel_hi:[1,0]
	v_pk_add_f32 v[106:107], v[106:107], 1.0 op_sel_hi:[1,0]
	v_exp_f32_e32 v97, v97
	v_ashrrev_i32_e32 v113, 31, v112
	v_rcp_f32_e32 v109, v109
	s_nop 0
	v_mul_f32_e32 v109, 2.0, v109
	v_pk_add_f32 v[96:97], v[96:97], 1.0 op_sel_hi:[1,0]
	v_rcp_f32_e32 v108, v108
	s_nop 0
	v_mul_f32_e32 v108, 2.0, v108
	v_pk_add_f32 v[108:109], v[108:109], 1.0 op_sel_hi:[1,0] neg_lo:[1,0] neg_hi:[1,0]
	v_lshlrev_b64 v[112:113], 11, v[112:113]
	v_pk_add_f32 v[108:109], v[108:109], 1.0 op_sel_hi:[1,0]
	s_nop 0
	v_pk_mul_f32 v[108:109], v[110:111], v[108:109]
	v_rcp_f32_e32 v107, v107
	v_rcp_f32_e32 v106, v106
	v_mul_f32_e32 v105, 0x3d372713, v100
	v_mul_f32_e32 v105, v100, v105
	v_fma_f32 v105, v100, v105, v100
	v_mul_f32_e32 v105, 0x3f4c422a, v105
	v_add_f32_e32 v105, v105, v105
	v_mul_f32_e32 v105, 0x3fb8aa3b, v105
	v_pk_mul_f32 v[106:107], v[108:109], v[106:107]
	v_exp_f32_e32 v108, v105
	v_mul_f32_e32 v105, 0x3d372713, v101
	v_mul_f32_e32 v105, v101, v105
	v_fma_f32 v105, v101, v105, v101
	v_mul_f32_e32 v105, 0x3f4c422a, v105
	v_add_f32_e32 v105, v105, v105
	v_mul_f32_e32 v105, 0x3fb8aa3b, v105
	v_exp_f32_e32 v109, v105
	v_cvt_pk_bf16_f32 v105, v106, v107
	v_pk_mul_f32 v[100:101], v[100:101], 0.5 op_sel_hi:[1,0]
	v_pk_add_f32 v[106:107], v[108:109], 1.0 op_sel_hi:[1,0]
	s_nop 0
	s_nop 0
	v_rcp_f32_e32 v107, v107
	s_nop 0
	v_mul_f32_e32 v107, 2.0, v107
	v_rcp_f32_e32 v106, v106
	s_nop 0
	v_mul_f32_e32 v106, 2.0, v106
	v_pk_add_f32 v[106:107], v[106:107], 1.0 op_sel_hi:[1,0] neg_lo:[1,0] neg_hi:[1,0]
	s_nop 0
	v_pk_add_f32 v[106:107], v[106:107], 1.0 op_sel_hi:[1,0]
	s_nop 0
	v_pk_mul_f32 v[100:101], v[100:101], v[106:107]
	v_rcp_f32_e32 v97, v97
	v_rcp_f32_e32 v96, v96
	s_nop 0
	v_pk_mul_f32 v[96:97], v[100:101], v[96:97]
	v_mul_f32_e32 v100, 0x3d372713, v102
	v_mul_f32_e32 v101, 0x3d372713, v103
	v_mul_f32_e32 v100, v102, v100
	v_mul_f32_e32 v101, v103, v101
	v_fma_f32 v100, v102, v100, v102
	v_fma_f32 v101, v103, v101, v103
	v_mul_f32_e32 v100, 0x3f4c422a, v100
	v_mul_f32_e32 v101, 0x3f4c422a, v101
	v_add_f32_e32 v100, v100, v100
	v_add_f32_e32 v101, v101, v101
	v_mul_f32_e32 v100, 0x3fb8aa3b, v100
	v_mul_f32_e32 v101, 0x3fb8aa3b, v101
	v_exp_f32_e32 v100, v100
	v_exp_f32_e32 v101, v101
	v_cvt_pk_bf16_f32 v106, v96, v97
	v_mul_f32_e32 v96, 0xbfb8aa3b, v98
	v_mul_f32_e32 v97, 0xbfb8aa3b, v99
	v_pk_add_f32 v[100:101], v[100:101], 1.0 op_sel_hi:[1,0]
	v_pk_mul_f32 v[98:99], v[102:103], 0.5 op_sel_hi:[1,0]
	v_exp_f32_e32 v96, v96
	v_exp_f32_e32 v97, v97
	v_rcp_f32_e32 v101, v101
	s_nop 0
	v_mul_f32_e32 v101, 2.0, v101
	v_pk_add_f32 v[96:97], v[96:97], 1.0 op_sel_hi:[1,0]
	v_rcp_f32_e32 v100, v100
	s_nop 0
	v_mul_f32_e32 v100, 2.0, v100
	v_pk_add_f32 v[100:101], v[100:101], 1.0 op_sel_hi:[1,0] neg_lo:[1,0] neg_hi:[1,0]
	s_nop 0
	v_pk_add_f32 v[100:101], v[100:101], 1.0 op_sel_hi:[1,0]
	s_nop 0
	v_pk_mul_f32 v[98:99], v[98:99], v[100:101]
	v_rcp_f32_e32 v97, v97
	v_rcp_f32_e32 v96, v96
	s_nop 0
	v_pk_mul_f32 v[96:97], v[98:99], v[96:97]
	s_nop 0
	v_cvt_pk_bf16_f32 v107, v96, v97
	v_lshl_add_u64 v[96:97], s[8:9], 0, v[112:113]
	v_lshl_add_u64 v[96:97], v[144:145], 1, v[96:97]
	global_store_dwordx4 v[96:97], v[104:107], off nt
; __device__ __forceinline__ unsigned cvt_pk_bf16(float lo, float hi) { const f32x2 v = {lo, hi}; return __builtin_bit_cast(unsigned, __builtin_convertvector(v, bf16x2_t)); }
; __device__ __forceinline__ float sigm(float x) { return 1.0f / (1.0f + __expf(-x)); }
; __device__ __forceinline__ float gelu_t(float x) { float u = 0.7978845608028654f * (x + 0.044715f * x * x * x); return 0.5f * x * (1.0f + tanh_(u)); }
;     __device__ __forceinline__ void operator()(AccRef acc, const Unit& u, int wr, int wc, int fr, int fq) const {
;     ...
;             const int col0 = (pn - 17) * 128 + cw;
; #pragma unroll
;             for (int ai = 0; ai < 2; ++ai)
; #pragma unroll
;                 for (int m = 0; m < 4; ++m) {
;                     const f32x4 g0 = acc[ai][0][m][0], g1 = acc[ai][0][m][1], s0 = acc[ai][1][m][0], s1 = acc[ai][1][m][1];
;                     u32x4 w;
;                     w.x = cvt_pk_bf16(gelu_t(g0[0]) * sigm(s0[0]), gelu_t(g0[1]) * sigm(s0[1])); w.y = cvt_pk_bf16(gelu_t(g0[2]) * sigm(s0[2]), gelu_t(g0[3]) * sigm(s0[3]));
;                     w.z = cvt_pk_bf16(gelu_t(g1[0]) * sigm(s1[0]), gelu_t(g1[1]) * sigm(s1[1])); w.w = cvt_pk_bf16(gelu_t(g1[2]) * sigm(s1[2]), gelu_t(g1[3]) * sigm(s1[3]));
;                     if (EPI_ROWS(ai, m) < MT) *(u32x4*)(GG + (size_t)EPI_ROWS(ai, m) * D + col0) = w;
.LBB0_598:
	s_or_b64 exec, exec, s[2:3]
	v_or_b32_e32 v96, 32, v128
	v_cmp_gt_i32_e32 vcc, s91, v96
	s_and_saveexec_b64 s[2:3], vcc
	s_cbranch_execz .LBB0_600
	v_mul_f32_e32 v98, 0x3d372713, v92
	v_mul_f32_e32 v99, 0x3d372713, v93
	v_mul_f32_e32 v98, v92, v98
	v_mul_f32_e32 v99, v93, v99
	v_fma_f32 v98, v92, v98, v92
	v_fma_f32 v99, v93, v99, v93
	v_mul_f32_e32 v98, 0x3f4c422a, v98
	v_mul_f32_e32 v99, 0x3f4c422a, v99
	v_add_f32_e32 v98, v98, v98
	v_add_f32_e32 v99, v99, v99
	v_mul_f32_e32 v98, 0x3fb8aa3b, v98
	v_mul_f32_e32 v99, 0x3fb8aa3b, v99
	v_exp_f32_e32 v98, v98
	v_exp_f32_e32 v99, v99
	v_mul_f32_e32 v88, 0xbfb8aa3b, v88
	v_mul_f32_e32 v89, 0xbfb8aa3b, v89
	v_exp_f32_e32 v88, v88
	v_pk_add_f32 v[98:99], v[98:99], 1.0 op_sel_hi:[1,0]
	v_exp_f32_e32 v89, v89
	s_nop 0
	v_pk_add_f32 v[88:89], v[88:89], 1.0 op_sel_hi:[1,0]
	v_pk_mul_f32 v[92:93], v[92:93], 0.5 op_sel_hi:[1,0]
	v_mul_f32_e32 v91, 0xbfb8aa3b, v91
	v_rcp_f32_e32 v99, v99
	s_nop 0
	v_mul_f32_e32 v99, 2.0, v99
	v_exp_f32_e32 v91, v91
	v_rcp_f32_e32 v98, v98
	s_nop 0
	v_mul_f32_e32 v98, 2.0, v98
	v_pk_add_f32 v[98:99], v[98:99], 1.0 op_sel_hi:[1,0] neg_lo:[1,0] neg_hi:[1,0]
	v_mul_f32_e32 v80, 0xbfb8aa3b, v80
	v_pk_add_f32 v[98:99], v[98:99], 1.0 op_sel_hi:[1,0]
	v_mul_f32_e32 v81, 0xbfb8aa3b, v81
	v_pk_mul_f32 v[92:93], v[92:93], v[98:99]
	v_rcp_f32_e32 v89, v89
	v_exp_f32_e32 v80, v80
	v_rcp_f32_e32 v88, v88
	s_nop 0
	v_pk_mul_f32 v[88:89], v[92:93], v[88:89]
	v_mul_f32_e32 v92, 0x3d372713, v94
	v_mul_f32_e32 v93, 0x3d372713, v95
	v_mul_f32_e32 v92, v94, v92
	v_mul_f32_e32 v93, v95, v93
	v_fma_f32 v92, v94, v92, v94
	v_fma_f32 v93, v95, v93, v95
	v_mul_f32_e32 v92, 0x3f4c422a, v92
	v_mul_f32_e32 v93, 0x3f4c422a, v93
	v_add_f32_e32 v92, v92, v92
	v_add_f32_e32 v93, v93, v93
	v_mul_f32_e32 v92, 0x3fb8aa3b, v92
	v_mul_f32_e32 v93, 0x3fb8aa3b, v93
	v_exp_f32_e32 v92, v92
	v_exp_f32_e32 v93, v93
	v_cvt_pk_bf16_f32 v88, v88, v89
	v_mul_f32_e32 v89, 0xbfb8aa3b, v90
	v_exp_f32_e32 v90, v89
	v_pk_add_f32 v[92:93], v[92:93], 1.0 op_sel_hi:[1,0]
	v_pk_mul_f32 v[94:95], v[94:95], 0.5 op_sel_hi:[1,0]
	v_pk_add_f32 v[90:91], v[90:91], 1.0 op_sel_hi:[1,0]
	v_exp_f32_e32 v81, v81
	v_ashrrev_i32_e32 v97, 31, v96
	v_rcp_f32_e32 v93, v93
	s_nop 0
	v_mul_f32_e32 v93, 2.0, v93
	v_pk_add_f32 v[80:81], v[80:81], 1.0 op_sel_hi:[1,0]
	v_rcp_f32_e32 v92, v92
	s_nop 0
	v_mul_f32_e32 v92, 2.0, v92
	v_pk_add_f32 v[92:93], v[92:93], 1.0 op_sel_hi:[1,0] neg_lo:[1,0] neg_hi:[1,0]
	v_lshlrev_b64 v[96:97], 11, v[96:97]
	v_pk_add_f32 v[92:93], v[92:93], 1.0 op_sel_hi:[1,0]
	s_nop 0
	v_pk_mul_f32 v[92:93], v[94:95], v[92:93]
	v_rcp_f32_e32 v91, v91
	v_rcp_f32_e32 v90, v90
	v_mul_f32_e32 v89, 0x3d372713, v84
	v_mul_f32_e32 v89, v84, v89
	v_fma_f32 v89, v84, v89, v84
	v_mul_f32_e32 v89, 0x3f4c422a, v89
	v_add_f32_e32 v89, v89, v89
	v_mul_f32_e32 v89, 0x3fb8aa3b, v89
	v_pk_mul_f32 v[90:91], v[92:93], v[90:91]
	v_exp_f32_e32 v92, v89
	v_mul_f32_e32 v89, 0x3d372713, v85
	v_mul_f32_e32 v89, v85, v89
	v_fma_f32 v89, v85, v89, v85
	v_mul_f32_e32 v89, 0x3f4c422a, v89
	v_add_f32_e32 v89, v89, v89
	v_mul_f32_e32 v89, 0x3fb8aa3b, v89
	v_exp_f32_e32 v93, v89
	v_cvt_pk_bf16_f32 v89, v90, v91
	v_pk_mul_f32 v[84:85], v[84:85], 0.5 op_sel_hi:[1,0]
	v_pk_add_f32 v[90:91], v[92:93], 1.0 op_sel_hi:[1,0]
	s_nop 0
	s_nop 0
	v_rcp_f32_e32 v91, v91
	s_nop 0
	v_mul_f32_e32 v91, 2.0, v91
	v_rcp_f32_e32 v90, v90
	s_nop 0
	v_mul_f32_e32 v90, 2.0, v90
	v_pk_add_f32 v[90:91], v[90:91], 1.0 op_sel_hi:[1,0] neg_lo:[1,0] neg_hi:[1,0]
	s_nop 0
	v_pk_add_f32 v[90:91], v[90:91], 1.0 op_sel_hi:[1,0]
	s_nop 0
	v_pk_mul_f32 v[84:85], v[84:85], v[90:91]
	v_rcp_f32_e32 v81, v81
	v_rcp_f32_e32 v80, v80
	s_nop 0
	v_pk_mul_f32 v[80:81], v[84:85], v[80:81]
	v_mul_f32_e32 v84, 0x3d372713, v86
	v_mul_f32_e32 v85, 0x3d372713, v87
	v_mul_f32_e32 v84, v86, v84
	v_mul_f32_e32 v85, v87, v85
	v_fma_f32 v84, v86, v84, v86
	v_fma_f32 v85, v87, v85, v87
	v_mul_f32_e32 v84, 0x3f4c422a, v84
	v_mul_f32_e32 v85, 0x3f4c422a, v85
	v_add_f32_e32 v84, v84, v84
	v_add_f32_e32 v85, v85, v85
	v_mul_f32_e32 v84, 0x3fb8aa3b, v84
	v_mul_f32_e32 v85, 0x3fb8aa3b, v85
	v_exp_f32_e32 v84, v84
	v_exp_f32_e32 v85, v85
	v_cvt_pk_bf16_f32 v90, v80, v81
	v_mul_f32_e32 v80, 0xbfb8aa3b, v82
	v_mul_f32_e32 v81, 0xbfb8aa3b, v83
	v_pk_add_f32 v[84:85], v[84:85], 1.0 op_sel_hi:[1,0]
	v_pk_mul_f32 v[82:83], v[86:87], 0.5 op_sel_hi:[1,0]
	v_exp_f32_e32 v80, v80
	v_exp_f32_e32 v81, v81
	v_rcp_f32_e32 v85, v85
	s_nop 0
	v_mul_f32_e32 v85, 2.0, v85
	v_pk_add_f32 v[80:81], v[80:81], 1.0 op_sel_hi:[1,0]
	v_rcp_f32_e32 v84, v84
	s_nop 0
	v_mul_f32_e32 v84, 2.0, v84
	v_pk_add_f32 v[84:85], v[84:85], 1.0 op_sel_hi:[1,0] neg_lo:[1,0] neg_hi:[1,0]
	s_nop 0
	v_pk_add_f32 v[84:85], v[84:85], 1.0 op_sel_hi:[1,0]
	s_nop 0
	v_pk_mul_f32 v[82:83], v[82:83], v[84:85]
	v_rcp_f32_e32 v81, v81
	v_rcp_f32_e32 v80, v80
	s_nop 0
	v_pk_mul_f32 v[80:81], v[82:83], v[80:81]
	s_nop 0
	v_cvt_pk_bf16_f32 v91, v80, v81
	v_lshl_add_u64 v[80:81], s[8:9], 0, v[96:97]
	v_lshl_add_u64 v[80:81], v[144:145], 1, v[80:81]
	global_store_dwordx4 v[80:81], v[88:91], off nt
; __device__ __forceinline__ unsigned cvt_pk_bf16(float lo, float hi) { const f32x2 v = {lo, hi}; return __builtin_bit_cast(unsigned, __builtin_convertvector(v, bf16x2_t)); }
; __device__ __forceinline__ float sigm(float x) { return 1.0f / (1.0f + __expf(-x)); }
; __device__ __forceinline__ float gelu_t(float x) { float u = 0.7978845608028654f * (x + 0.044715f * x * x * x); return 0.5f * x * (1.0f + tanh_(u)); }
;     __device__ __forceinline__ void operator()(AccRef acc, const Unit& u, int wr, int wc, int fr, int fq) const {
;     ...
;             const int col0 = (pn - 17) * 128 + cw;
; #pragma unroll
;             for (int ai = 0; ai < 2; ++ai)
; #pragma unroll
;                 for (int m = 0; m < 4; ++m) {
;                     const f32x4 g0 = acc[ai][0][m][0], g1 = acc[ai][0][m][1], s0 = acc[ai][1][m][0], s1 = acc[ai][1][m][1];
;                     u32x4 w;
;                     w.x = cvt_pk_bf16(gelu_t(g0[0]) * sigm(s0[0]), gelu_t(g0[1]) * sigm(s0[1])); w.y = cvt_pk_bf16(gelu_t(g0[2]) * sigm(s0[2]), gelu_t(g0[3]) * sigm(s0[3]));
;                     w.z = cvt_pk_bf16(gelu_t(g1[0]) * sigm(s1[0]), gelu_t(g1[1]) * sigm(s1[1])); w.w = cvt_pk_bf16(gelu_t(g1[2]) * sigm(s1[2]), gelu_t(g1[3]) * sigm(s1[3]));
;                     if (EPI_ROWS(ai, m) < MT) *(u32x4*)(GG + (size_t)EPI_ROWS(ai, m) * D + col0) = w;
.LBB0_600:
	s_or_b64 exec, exec, s[2:3]
	v_or_b32_e32 v80, 48, v128
	v_cmp_gt_i32_e32 vcc, s91, v80
	s_and_saveexec_b64 s[2:3], vcc
	s_cbranch_execz .LBB0_602
	v_mul_f32_e32 v82, 0x3d372713, v76
	v_mul_f32_e32 v83, 0x3d372713, v77
	v_mul_f32_e32 v82, v76, v82
	v_mul_f32_e32 v83, v77, v83
	v_fma_f32 v82, v76, v82, v76
	v_fma_f32 v83, v77, v83, v77
	v_mul_f32_e32 v82, 0x3f4c422a, v82
	v_mul_f32_e32 v83, 0x3f4c422a, v83
	v_add_f32_e32 v82, v82, v82
	v_add_f32_e32 v83, v83, v83
	v_mul_f32_e32 v82, 0x3fb8aa3b, v82
	v_mul_f32_e32 v83, 0x3fb8aa3b, v83
	v_exp_f32_e32 v82, v82
	v_exp_f32_e32 v83, v83
	v_mul_f32_e32 v72, 0xbfb8aa3b, v72
	v_mul_f32_e32 v73, 0xbfb8aa3b, v73
	v_exp_f32_e32 v72, v72
	v_pk_add_f32 v[82:83], v[82:83], 1.0 op_sel_hi:[1,0]
	v_exp_f32_e32 v73, v73
	s_nop 0
	v_pk_add_f32 v[72:73], v[72:73], 1.0 op_sel_hi:[1,0]
	v_pk_mul_f32 v[76:77], v[76:77], 0.5 op_sel_hi:[1,0]
	v_mul_f32_e32 v75, 0xbfb8aa3b, v75
	v_rcp_f32_e32 v83, v83
	s_nop 0
	v_mul_f32_e32 v83, 2.0, v83
	v_exp_f32_e32 v75, v75
	v_rcp_f32_e32 v82, v82
	s_nop 0
	v_mul_f32_e32 v82, 2.0, v82
	v_pk_add_f32 v[82:83], v[82:83], 1.0 op_sel_hi:[1,0] neg_lo:[1,0] neg_hi:[1,0]
	v_mul_f32_e32 v64, 0xbfb8aa3b, v64
	v_pk_add_f32 v[82:83], v[82:83], 1.0 op_sel_hi:[1,0]
	v_mul_f32_e32 v65, 0xbfb8aa3b, v65
	v_pk_mul_f32 v[76:77], v[76:77], v[82:83]
	v_rcp_f32_e32 v73, v73
	v_exp_f32_e32 v64, v64
	v_rcp_f32_e32 v72, v72
	s_nop 0
	v_pk_mul_f32 v[72:73], v[76:77], v[72:73]
	v_mul_f32_e32 v76, 0x3d372713, v78
	v_mul_f32_e32 v77, 0x3d372713, v79
	v_mul_f32_e32 v76, v78, v76
	v_mul_f32_e32 v77, v79, v77
	v_fma_f32 v76, v78, v76, v78
	v_fma_f32 v77, v79, v77, v79
	v_mul_f32_e32 v76, 0x3f4c422a, v76
	v_mul_f32_e32 v77, 0x3f4c422a, v77
	v_add_f32_e32 v76, v76, v76
	v_add_f32_e32 v77, v77, v77
	v_mul_f32_e32 v76, 0x3fb8aa3b, v76
	v_mul_f32_e32 v77, 0x3fb8aa3b, v77
	v_exp_f32_e32 v76, v76
	v_exp_f32_e32 v77, v77
	v_cvt_pk_bf16_f32 v72, v72, v73
	v_mul_f32_e32 v73, 0xbfb8aa3b, v74
	v_exp_f32_e32 v74, v73
	v_pk_add_f32 v[76:77], v[76:77], 1.0 op_sel_hi:[1,0]
	v_pk_mul_f32 v[78:79], v[78:79], 0.5 op_sel_hi:[1,0]
	v_pk_add_f32 v[74:75], v[74:75], 1.0 op_sel_hi:[1,0]
	v_exp_f32_e32 v65, v65
	v_ashrrev_i32_e32 v81, 31, v80
	v_rcp_f32_e32 v77, v77
	s_nop 0
	v_mul_f32_e32 v77, 2.0, v77
	v_pk_add_f32 v[64:65], v[64:65], 1.0 op_sel_hi:[1,0]
	v_rcp_f32_e32 v76, v76
	s_nop 0
	v_mul_f32_e32 v76, 2.0, v76
	v_pk_add_f32 v[76:77], v[76:77], 1.0 op_sel_hi:[1,0] neg_lo:[1,0] neg_hi:[1,0]
	v_lshlrev_b64 v[80:81], 11, v[80:81]
	v_pk_add_f32 v[76:77], v[76:77], 1.0 op_sel_hi:[1,0]
	s_nop 0
	v_pk_mul_f32 v[76:77], v[78:79], v[76:77]
	v_rcp_f32_e32 v75, v75
	v_rcp_f32_e32 v74, v74
	v_mul_f32_e32 v73, 0x3d372713, v68
	v_mul_f32_e32 v73, v68, v73
	v_fma_f32 v73, v68, v73, v68
	v_mul_f32_e32 v73, 0x3f4c422a, v73
	v_add_f32_e32 v73, v73, v73
	v_mul_f32_e32 v73, 0x3fb8aa3b, v73
	v_pk_mul_f32 v[74:75], v[76:77], v[74:75]
	v_exp_f32_e32 v76, v73
	v_mul_f32_e32 v73, 0x3d372713, v69
	v_mul_f32_e32 v73, v69, v73
	v_fma_f32 v73, v69, v73, v69
	v_mul_f32_e32 v73, 0x3f4c422a, v73
	v_add_f32_e32 v73, v73, v73
	v_mul_f32_e32 v73, 0x3fb8aa3b, v73
	v_exp_f32_e32 v77, v73
	v_cvt_pk_bf16_f32 v73, v74, v75
	v_pk_mul_f32 v[68:69], v[68:69], 0.5 op_sel_hi:[1,0]
	v_pk_add_f32 v[74:75], v[76:77], 1.0 op_sel_hi:[1,0]
	s_nop 0
	s_nop 0
	v_rcp_f32_e32 v75, v75
	s_nop 0
	v_mul_f32_e32 v75, 2.0, v75
	v_rcp_f32_e32 v74, v74
	s_nop 0
	v_mul_f32_e32 v74, 2.0, v74
	v_pk_add_f32 v[74:75], v[74:75], 1.0 op_sel_hi:[1,0] neg_lo:[1,0] neg_hi:[1,0]
	s_nop 0
	v_pk_add_f32 v[74:75], v[74:75], 1.0 op_sel_hi:[1,0]
	s_nop 0
	v_pk_mul_f32 v[68:69], v[68:69], v[74:75]
	v_rcp_f32_e32 v65, v65
	v_rcp_f32_e32 v64, v64
	s_nop 0
	v_pk_mul_f32 v[64:65], v[68:69], v[64:65]
	v_mul_f32_e32 v68, 0x3d372713, v70
	v_mul_f32_e32 v69, 0x3d372713, v71
	v_mul_f32_e32 v68, v70, v68
	v_mul_f32_e32 v69, v71, v69
	v_fma_f32 v68, v70, v68, v70
	v_fma_f32 v69, v71, v69, v71
	v_mul_f32_e32 v68, 0x3f4c422a, v68
	v_mul_f32_e32 v69, 0x3f4c422a, v69
	v_add_f32_e32 v68, v68, v68
	v_add_f32_e32 v69, v69, v69
	v_mul_f32_e32 v68, 0x3fb8aa3b, v68
	v_mul_f32_e32 v69, 0x3fb8aa3b, v69
	v_exp_f32_e32 v68, v68
	v_exp_f32_e32 v69, v69
	v_cvt_pk_bf16_f32 v74, v64, v65
	v_mul_f32_e32 v64, 0xbfb8aa3b, v66
	v_mul_f32_e32 v65, 0xbfb8aa3b, v67
	v_pk_add_f32 v[68:69], v[68:69], 1.0 op_sel_hi:[1,0]
	v_pk_mul_f32 v[66:67], v[70:71], 0.5 op_sel_hi:[1,0]
	v_exp_f32_e32 v64, v64
	v_exp_f32_e32 v65, v65
	v_rcp_f32_e32 v69, v69
	s_nop 0
	v_mul_f32_e32 v69, 2.0, v69
	v_pk_add_f32 v[64:65], v[64:65], 1.0 op_sel_hi:[1,0]
	v_rcp_f32_e32 v68, v68
	s_nop 0
	v_mul_f32_e32 v68, 2.0, v68
	v_pk_add_f32 v[68:69], v[68:69], 1.0 op_sel_hi:[1,0] neg_lo:[1,0] neg_hi:[1,0]
	s_nop 0
	v_pk_add_f32 v[68:69], v[68:69], 1.0 op_sel_hi:[1,0]
	s_nop 0
	v_pk_mul_f32 v[66:67], v[66:67], v[68:69]
	v_rcp_f32_e32 v65, v65
	v_rcp_f32_e32 v64, v64
	s_nop 0
	v_pk_mul_f32 v[64:65], v[66:67], v[64:65]
	s_nop 0
	v_cvt_pk_bf16_f32 v75, v64, v65
	v_lshl_add_u64 v[64:65], s[8:9], 0, v[80:81]
	v_lshl_add_u64 v[64:65], v[144:145], 1, v[64:65]
	global_store_dwordx4 v[64:65], v[72:75], off nt
; __device__ __forceinline__ unsigned cvt_pk_bf16(float lo, float hi) { const f32x2 v = {lo, hi}; return __builtin_bit_cast(unsigned, __builtin_convertvector(v, bf16x2_t)); }
; __device__ __forceinline__ float sigm(float x) { return 1.0f / (1.0f + __expf(-x)); }
; __device__ __forceinline__ float gelu_t(float x) { float u = 0.7978845608028654f * (x + 0.044715f * x * x * x); return 0.5f * x * (1.0f + tanh_(u)); }
;     __device__ __forceinline__ void operator()(AccRef acc, const Unit& u, int wr, int wc, int fr, int fq) const {
;     ...
;             const int col0 = (pn - 17) * 128 + cw;
; #pragma unroll
;             for (int ai = 0; ai < 2; ++ai)
; #pragma unroll
;                 for (int m = 0; m < 4; ++m) {
;                     const f32x4 g0 = acc[ai][0][m][0], g1 = acc[ai][0][m][1], s0 = acc[ai][1][m][0], s1 = acc[ai][1][m][1];
;                     u32x4 w;
;                     w.x = cvt_pk_bf16(gelu_t(g0[0]) * sigm(s0[0]), gelu_t(g0[1]) * sigm(s0[1])); w.y = cvt_pk_bf16(gelu_t(g0[2]) * sigm(s0[2]), gelu_t(g0[3]) * sigm(s0[3]));
;                     w.z = cvt_pk_bf16(gelu_t(g1[0]) * sigm(s1[0]), gelu_t(g1[1]) * sigm(s1[1])); w.w = cvt_pk_bf16(gelu_t(g1[2]) * sigm(s1[2]), gelu_t(g1[3]) * sigm(s1[3]));
;                     if (EPI_ROWS(ai, m) < MT) *(u32x4*)(GG + (size_t)EPI_ROWS(ai, m) * D + col0) = w;
.LBB0_602:
	s_or_b64 exec, exec, s[2:3]
	v_add_u32_e32 v64, 0x80, v128
	v_cmp_gt_i32_e32 vcc, s91, v64
	s_and_saveexec_b64 s[2:3], vcc
	s_cbranch_execz .LBB0_604
	v_mul_f32_e32 v66, 0x3d372713, v60
	v_mul_f32_e32 v67, 0x3d372713, v61
	v_mul_f32_e32 v66, v60, v66
	v_mul_f32_e32 v67, v61, v67
	v_fma_f32 v66, v60, v66, v60
	v_fma_f32 v67, v61, v67, v61
	v_mul_f32_e32 v66, 0x3f4c422a, v66
	v_mul_f32_e32 v67, 0x3f4c422a, v67
	v_add_f32_e32 v66, v66, v66
	v_add_f32_e32 v67, v67, v67
	v_mul_f32_e32 v66, 0x3fb8aa3b, v66
	v_mul_f32_e32 v67, 0x3fb8aa3b, v67
	v_exp_f32_e32 v66, v66
	v_exp_f32_e32 v67, v67
	v_mul_f32_e32 v56, 0xbfb8aa3b, v56
	v_mul_f32_e32 v57, 0xbfb8aa3b, v57
	v_exp_f32_e32 v56, v56
	v_pk_add_f32 v[66:67], v[66:67], 1.0 op_sel_hi:[1,0]
	v_exp_f32_e32 v57, v57
	s_nop 0
	v_pk_add_f32 v[56:57], v[56:57], 1.0 op_sel_hi:[1,0]
	v_pk_mul_f32 v[60:61], v[60:61], 0.5 op_sel_hi:[1,0]
	v_mul_f32_e32 v59, 0xbfb8aa3b, v59
	v_rcp_f32_e32 v67, v67
	s_nop 0
	v_mul_f32_e32 v67, 2.0, v67
	v_exp_f32_e32 v59, v59
	v_rcp_f32_e32 v66, v66
	s_nop 0
	v_mul_f32_e32 v66, 2.0, v66
	v_pk_add_f32 v[66:67], v[66:67], 1.0 op_sel_hi:[1,0] neg_lo:[1,0] neg_hi:[1,0]
	v_mul_f32_e32 v48, 0xbfb8aa3b, v48
	v_pk_add_f32 v[66:67], v[66:67], 1.0 op_sel_hi:[1,0]
	v_mul_f32_e32 v49, 0xbfb8aa3b, v49
	v_pk_mul_f32 v[60:61], v[60:61], v[66:67]
	v_rcp_f32_e32 v57, v57
	v_exp_f32_e32 v48, v48
	v_rcp_f32_e32 v56, v56
	s_nop 0
	v_pk_mul_f32 v[56:57], v[60:61], v[56:57]
	v_mul_f32_e32 v60, 0x3d372713, v62
	v_mul_f32_e32 v61, 0x3d372713, v63
	v_mul_f32_e32 v60, v62, v60
	v_mul_f32_e32 v61, v63, v61
	v_fma_f32 v60, v62, v60, v62
	v_fma_f32 v61, v63, v61, v63
	v_mul_f32_e32 v60, 0x3f4c422a, v60
	v_mul_f32_e32 v61, 0x3f4c422a, v61
	v_add_f32_e32 v60, v60, v60
	v_add_f32_e32 v61, v61, v61
	v_mul_f32_e32 v60, 0x3fb8aa3b, v60
	v_mul_f32_e32 v61, 0x3fb8aa3b, v61
	v_exp_f32_e32 v60, v60
	v_exp_f32_e32 v61, v61
	v_cvt_pk_bf16_f32 v56, v56, v57
	v_mul_f32_e32 v57, 0xbfb8aa3b, v58
	v_exp_f32_e32 v58, v57
	v_pk_add_f32 v[60:61], v[60:61], 1.0 op_sel_hi:[1,0]
	v_pk_mul_f32 v[62:63], v[62:63], 0.5 op_sel_hi:[1,0]
	v_pk_add_f32 v[58:59], v[58:59], 1.0 op_sel_hi:[1,0]
	v_exp_f32_e32 v49, v49
	v_ashrrev_i32_e32 v65, 31, v64
	v_rcp_f32_e32 v61, v61
	s_nop 0
	v_mul_f32_e32 v61, 2.0, v61
	v_pk_add_f32 v[48:49], v[48:49], 1.0 op_sel_hi:[1,0]
	v_rcp_f32_e32 v60, v60
	s_nop 0
	v_mul_f32_e32 v60, 2.0, v60
	v_pk_add_f32 v[60:61], v[60:61], 1.0 op_sel_hi:[1,0] neg_lo:[1,0] neg_hi:[1,0]
	v_lshlrev_b64 v[64:65], 11, v[64:65]
	v_pk_add_f32 v[60:61], v[60:61], 1.0 op_sel_hi:[1,0]
	s_nop 0
	v_pk_mul_f32 v[60:61], v[62:63], v[60:61]
	v_rcp_f32_e32 v59, v59
	v_rcp_f32_e32 v58, v58
	v_mul_f32_e32 v57, 0x3d372713, v52
	v_mul_f32_e32 v57, v52, v57
	v_fma_f32 v57, v52, v57, v52
	v_mul_f32_e32 v57, 0x3f4c422a, v57
	v_add_f32_e32 v57, v57, v57
	v_mul_f32_e32 v57, 0x3fb8aa3b, v57
	v_pk_mul_f32 v[58:59], v[60:61], v[58:59]
	v_exp_f32_e32 v60, v57
	v_mul_f32_e32 v57, 0x3d372713, v53
	v_mul_f32_e32 v57, v53, v57
	v_fma_f32 v57, v53, v57, v53
	v_mul_f32_e32 v57, 0x3f4c422a, v57
	v_add_f32_e32 v57, v57, v57
	v_mul_f32_e32 v57, 0x3fb8aa3b, v57
	v_exp_f32_e32 v61, v57
	v_cvt_pk_bf16_f32 v57, v58, v59
	v_pk_mul_f32 v[52:53], v[52:53], 0.5 op_sel_hi:[1,0]
	v_pk_add_f32 v[58:59], v[60:61], 1.0 op_sel_hi:[1,0]
	s_nop 0
	s_nop 0
	v_rcp_f32_e32 v59, v59
	s_nop 0
	v_mul_f32_e32 v59, 2.0, v59
	v_rcp_f32_e32 v58, v58
	s_nop 0
	v_mul_f32_e32 v58, 2.0, v58
	v_pk_add_f32 v[58:59], v[58:59], 1.0 op_sel_hi:[1,0] neg_lo:[1,0] neg_hi:[1,0]
	s_nop 0
	v_pk_add_f32 v[58:59], v[58:59], 1.0 op_sel_hi:[1,0]
	s_nop 0
	v_pk_mul_f32 v[52:53], v[52:53], v[58:59]
	v_rcp_f32_e32 v49, v49
	v_rcp_f32_e32 v48, v48
	s_nop 0
	v_pk_mul_f32 v[48:49], v[52:53], v[48:49]
	v_mul_f32_e32 v52, 0x3d372713, v54
	v_mul_f32_e32 v53, 0x3d372713, v55
	v_mul_f32_e32 v52, v54, v52
	v_mul_f32_e32 v53, v55, v53
	v_fma_f32 v52, v54, v52, v54
	v_fma_f32 v53, v55, v53, v55
	v_mul_f32_e32 v52, 0x3f4c422a, v52
	v_mul_f32_e32 v53, 0x3f4c422a, v53
	v_add_f32_e32 v52, v52, v52
	v_add_f32_e32 v53, v53, v53
	v_mul_f32_e32 v52, 0x3fb8aa3b, v52
	v_mul_f32_e32 v53, 0x3fb8aa3b, v53
	v_exp_f32_e32 v52, v52
	v_exp_f32_e32 v53, v53
	v_cvt_pk_bf16_f32 v58, v48, v49
	v_mul_f32_e32 v48, 0xbfb8aa3b, v50
	v_mul_f32_e32 v49, 0xbfb8aa3b, v51
	v_pk_add_f32 v[52:53], v[52:53], 1.0 op_sel_hi:[1,0]
	v_pk_mul_f32 v[50:51], v[54:55], 0.5 op_sel_hi:[1,0]
	v_exp_f32_e32 v48, v48
	v_exp_f32_e32 v49, v49
	v_rcp_f32_e32 v53, v53
	s_nop 0
	v_mul_f32_e32 v53, 2.0, v53
	v_pk_add_f32 v[48:49], v[48:49], 1.0 op_sel_hi:[1,0]
	v_rcp_f32_e32 v52, v52
	s_nop 0
	v_mul_f32_e32 v52, 2.0, v52
	v_pk_add_f32 v[52:53], v[52:53], 1.0 op_sel_hi:[1,0] neg_lo:[1,0] neg_hi:[1,0]
	s_nop 0
	v_pk_add_f32 v[52:53], v[52:53], 1.0 op_sel_hi:[1,0]
	s_nop 0
	v_pk_mul_f32 v[50:51], v[50:51], v[52:53]
	v_rcp_f32_e32 v49, v49
	v_rcp_f32_e32 v48, v48
	s_nop 0
	v_pk_mul_f32 v[48:49], v[50:51], v[48:49]
	s_nop 0
	v_cvt_pk_bf16_f32 v59, v48, v49
	v_lshl_add_u64 v[48:49], s[8:9], 0, v[64:65]
	v_lshl_add_u64 v[48:49], v[144:145], 1, v[48:49]
	global_store_dwordx4 v[48:49], v[56:59], off nt
; __device__ __forceinline__ unsigned cvt_pk_bf16(float lo, float hi) { const f32x2 v = {lo, hi}; return __builtin_bit_cast(unsigned, __builtin_convertvector(v, bf16x2_t)); }
; __device__ __forceinline__ float sigm(float x) { return 1.0f / (1.0f + __expf(-x)); }
; __device__ __forceinline__ float gelu_t(float x) { float u = 0.7978845608028654f * (x + 0.044715f * x * x * x); return 0.5f * x * (1.0f + tanh_(u)); }
;     __device__ __forceinline__ void operator()(AccRef acc, const Unit& u, int wr, int wc, int fr, int fq) const {
;     ...
;                     const f32x4 g0 = acc[ai][0][m][0], g1 = acc[ai][0][m][1], s0 = acc[ai][1][m][0], s1 = acc[ai][1][m][1];
;                     u32x4 w;
;                     w.x = cvt_pk_bf16(gelu_t(g0[0]) * sigm(s0[0]), gelu_t(g0[1]) * sigm(s0[1])); w.y = cvt_pk_bf16(gelu_t(g0[2]) * sigm(s0[2]), gelu_t(g0[3]) * sigm(s0[3]));
;                     w.z = cvt_pk_bf16(gelu_t(g1[0]) * sigm(s1[0]), gelu_t(g1[1]) * sigm(s1[1])); w.w = cvt_pk_bf16(gelu_t(g1[2]) * sigm(s1[2]), gelu_t(g1[3]) * sigm(s1[3]));
;                     if (EPI_ROWS(ai, m) < MT) *(u32x4*)(GG + (size_t)EPI_ROWS(ai, m) * D + col0) = w;
.LBB0_604:
	s_or_b64 exec, exec, s[2:3]
	v_add_u32_e32 v48, 0x90, v128
	v_cmp_gt_i32_e32 vcc, s91, v48
	s_and_saveexec_b64 s[2:3], vcc
	s_cbranch_execz .LBB0_606
	v_mul_f32_e32 v50, 0x3d372713, v44
	v_mul_f32_e32 v51, 0x3d372713, v45
	v_mul_f32_e32 v50, v44, v50
	v_mul_f32_e32 v51, v45, v51
	v_fma_f32 v50, v44, v50, v44
	v_fma_f32 v51, v45, v51, v45
	v_mul_f32_e32 v50, 0x3f4c422a, v50
	v_mul_f32_e32 v51, 0x3f4c422a, v51
	v_add_f32_e32 v50, v50, v50
	v_add_f32_e32 v51, v51, v51
	v_mul_f32_e32 v50, 0x3fb8aa3b, v50
	v_mul_f32_e32 v51, 0x3fb8aa3b, v51
	v_exp_f32_e32 v50, v50
	v_exp_f32_e32 v51, v51
	v_mul_f32_e32 v40, 0xbfb8aa3b, v40
	v_mul_f32_e32 v41, 0xbfb8aa3b, v41
	v_exp_f32_e32 v40, v40
	v_pk_add_f32 v[50:51], v[50:51], 1.0 op_sel_hi:[1,0]
	v_exp_f32_e32 v41, v41
	s_nop 0
	v_pk_add_f32 v[40:41], v[40:41], 1.0 op_sel_hi:[1,0]
	v_pk_mul_f32 v[44:45], v[44:45], 0.5 op_sel_hi:[1,0]
	v_mul_f32_e32 v43, 0xbfb8aa3b, v43
	v_rcp_f32_e32 v51, v51
	s_nop 0
	v_mul_f32_e32 v51, 2.0, v51
	v_exp_f32_e32 v43, v43
	v_rcp_f32_e32 v50, v50
	s_nop 0
	v_mul_f32_e32 v50, 2.0, v50
	v_pk_add_f32 v[50:51], v[50:51], 1.0 op_sel_hi:[1,0] neg_lo:[1,0] neg_hi:[1,0]
	v_mul_f32_e32 v32, 0xbfb8aa3b, v32
	v_pk_add_f32 v[50:51], v[50:51], 1.0 op_sel_hi:[1,0]
	v_mul_f32_e32 v33, 0xbfb8aa3b, v33
	v_pk_mul_f32 v[44:45], v[44:45], v[50:51]
	v_rcp_f32_e32 v41, v41
	v_exp_f32_e32 v32, v32
	v_rcp_f32_e32 v40, v40
	s_nop 0
	v_pk_mul_f32 v[40:41], v[44:45], v[40:41]
	v_mul_f32_e32 v44, 0x3d372713, v46
	v_mul_f32_e32 v45, 0x3d372713, v47
	v_mul_f32_e32 v44, v46, v44
	v_mul_f32_e32 v45, v47, v45
	v_fma_f32 v44, v46, v44, v46
	v_fma_f32 v45, v47, v45, v47
	v_mul_f32_e32 v44, 0x3f4c422a, v44
	v_mul_f32_e32 v45, 0x3f4c422a, v45
	v_add_f32_e32 v44, v44, v44
	v_add_f32_e32 v45, v45, v45
	v_mul_f32_e32 v44, 0x3fb8aa3b, v44
	v_mul_f32_e32 v45, 0x3fb8aa3b, v45
	v_exp_f32_e32 v44, v44
	v_exp_f32_e32 v45, v45
	v_cvt_pk_bf16_f32 v40, v40, v41
	v_mul_f32_e32 v41, 0xbfb8aa3b, v42
	v_exp_f32_e32 v42, v41
	v_pk_add_f32 v[44:45], v[44:45], 1.0 op_sel_hi:[1,0]
	v_pk_mul_f32 v[46:47], v[46:47], 0.5 op_sel_hi:[1,0]
	v_pk_add_f32 v[42:43], v[42:43], 1.0 op_sel_hi:[1,0]
	v_exp_f32_e32 v33, v33
	v_ashrrev_i32_e32 v49, 31, v48
	v_rcp_f32_e32 v45, v45
	s_nop 0
	v_mul_f32_e32 v45, 2.0, v45
	v_pk_add_f32 v[32:33], v[32:33], 1.0 op_sel_hi:[1,0]
	v_rcp_f32_e32 v44, v44
	s_nop 0
	v_mul_f32_e32 v44, 2.0, v44
	v_pk_add_f32 v[44:45], v[44:45], 1.0 op_sel_hi:[1,0] neg_lo:[1,0] neg_hi:[1,0]
	v_lshlrev_b64 v[48:49], 11, v[48:49]
	v_pk_add_f32 v[44:45], v[44:45], 1.0 op_sel_hi:[1,0]
	s_nop 0
	v_pk_mul_f32 v[44:45], v[46:47], v[44:45]
	v_rcp_f32_e32 v43, v43
	v_rcp_f32_e32 v42, v42
	v_mul_f32_e32 v41, 0x3d372713, v36
	v_mul_f32_e32 v41, v36, v41
	v_fma_f32 v41, v36, v41, v36
	v_mul_f32_e32 v41, 0x3f4c422a, v41
	v_add_f32_e32 v41, v41, v41
	v_mul_f32_e32 v41, 0x3fb8aa3b, v41
	v_pk_mul_f32 v[42:43], v[44:45], v[42:43]
	v_exp_f32_e32 v44, v41
	v_mul_f32_e32 v41, 0x3d372713, v37
	v_mul_f32_e32 v41, v37, v41
	v_fma_f32 v41, v37, v41, v37
	v_mul_f32_e32 v41, 0x3f4c422a, v41
	v_add_f32_e32 v41, v41, v41
	v_mul_f32_e32 v41, 0x3fb8aa3b, v41
	v_exp_f32_e32 v45, v41
	v_cvt_pk_bf16_f32 v41, v42, v43
	v_pk_mul_f32 v[36:37], v[36:37], 0.5 op_sel_hi:[1,0]
	v_pk_add_f32 v[42:43], v[44:45], 1.0 op_sel_hi:[1,0]
	s_nop 0
	s_nop 0
	v_rcp_f32_e32 v43, v43
	s_nop 0
	v_mul_f32_e32 v43, 2.0, v43
	v_rcp_f32_e32 v42, v42
	s_nop 0
	v_mul_f32_e32 v42, 2.0, v42
	v_pk_add_f32 v[42:43], v[42:43], 1.0 op_sel_hi:[1,0] neg_lo:[1,0] neg_hi:[1,0]
	s_nop 0
	v_pk_add_f32 v[42:43], v[42:43], 1.0 op_sel_hi:[1,0]
	s_nop 0
	v_pk_mul_f32 v[36:37], v[36:37], v[42:43]
	v_rcp_f32_e32 v33, v33
	v_rcp_f32_e32 v32, v32
	s_nop 0
	v_pk_mul_f32 v[32:33], v[36:37], v[32:33]
	v_mul_f32_e32 v36, 0x3d372713, v38
	v_mul_f32_e32 v37, 0x3d372713, v39
	v_mul_f32_e32 v36, v38, v36
	v_mul_f32_e32 v37, v39, v37
	v_fma_f32 v36, v38, v36, v38
	v_fma_f32 v37, v39, v37, v39
	v_mul_f32_e32 v36, 0x3f4c422a, v36
	v_mul_f32_e32 v37, 0x3f4c422a, v37
	v_add_f32_e32 v36, v36, v36
	v_add_f32_e32 v37, v37, v37
	v_mul_f32_e32 v36, 0x3fb8aa3b, v36
	v_mul_f32_e32 v37, 0x3fb8aa3b, v37
	v_exp_f32_e32 v36, v36
	v_exp_f32_e32 v37, v37
	v_cvt_pk_bf16_f32 v42, v32, v33
	v_mul_f32_e32 v32, 0xbfb8aa3b, v34
	v_mul_f32_e32 v33, 0xbfb8aa3b, v35
	v_pk_add_f32 v[36:37], v[36:37], 1.0 op_sel_hi:[1,0]
	v_pk_mul_f32 v[34:35], v[38:39], 0.5 op_sel_hi:[1,0]
	v_exp_f32_e32 v32, v32
	v_exp_f32_e32 v33, v33
	v_rcp_f32_e32 v37, v37
	s_nop 0
	v_mul_f32_e32 v37, 2.0, v37
	v_pk_add_f32 v[32:33], v[32:33], 1.0 op_sel_hi:[1,0]
	v_rcp_f32_e32 v36, v36
	s_nop 0
	v_mul_f32_e32 v36, 2.0, v36
	v_pk_add_f32 v[36:37], v[36:37], 1.0 op_sel_hi:[1,0] neg_lo:[1,0] neg_hi:[1,0]
	s_nop 0
	v_pk_add_f32 v[36:37], v[36:37], 1.0 op_sel_hi:[1,0]
	s_nop 0
	v_pk_mul_f32 v[34:35], v[34:35], v[36:37]
	v_rcp_f32_e32 v33, v33
	v_rcp_f32_e32 v32, v32
	s_nop 0
	v_pk_mul_f32 v[32:33], v[34:35], v[32:33]
	s_nop 0
	v_cvt_pk_bf16_f32 v43, v32, v33
	v_lshl_add_u64 v[32:33], s[8:9], 0, v[48:49]
	v_lshl_add_u64 v[32:33], v[144:145], 1, v[32:33]
	global_store_dwordx4 v[32:33], v[40:43], off nt
; __device__ __forceinline__ unsigned cvt_pk_bf16(float lo, float hi) { const f32x2 v = {lo, hi}; return __builtin_bit_cast(unsigned, __builtin_convertvector(v, bf16x2_t)); }
; __device__ __forceinline__ float sigm(float x) { return 1.0f / (1.0f + __expf(-x)); }
; __device__ __forceinline__ float gelu_t(float x) { float u = 0.7978845608028654f * (x + 0.044715f * x * x * x); return 0.5f * x * (1.0f + tanh_(u)); }
;     __device__ __forceinline__ void operator()(AccRef acc, const Unit& u, int wr, int wc, int fr, int fq) const {
;     ...
;                     const f32x4 g0 = acc[ai][0][m][0], g1 = acc[ai][0][m][1], s0 = acc[ai][1][m][0], s1 = acc[ai][1][m][1];
;                     u32x4 w;
;                     w.x = cvt_pk_bf16(gelu_t(g0[0]) * sigm(s0[0]), gelu_t(g0[1]) * sigm(s0[1])); w.y = cvt_pk_bf16(gelu_t(g0[2]) * sigm(s0[2]), gelu_t(g0[3]) * sigm(s0[3]));
;                     w.z = cvt_pk_bf16(gelu_t(g1[0]) * sigm(s1[0]), gelu_t(g1[1]) * sigm(s1[1])); w.w = cvt_pk_bf16(gelu_t(g1[2]) * sigm(s1[2]), gelu_t(g1[3]) * sigm(s1[3]));
;                     if (EPI_ROWS(ai, m) < MT) *(u32x4*)(GG + (size_t)EPI_ROWS(ai, m) * D + col0) = w;
.LBB0_606:
	s_or_b64 exec, exec, s[2:3]
	v_add_u32_e32 v32, 0xa0, v128
	v_cmp_gt_i32_e32 vcc, s91, v32
	s_and_saveexec_b64 s[2:3], vcc
	s_cbranch_execz .LBB0_608
	v_mul_f32_e32 v34, 0x3d372713, v28
	v_mul_f32_e32 v35, 0x3d372713, v29
	v_mul_f32_e32 v34, v28, v34
	v_mul_f32_e32 v35, v29, v35
	v_fma_f32 v34, v28, v34, v28
	v_fma_f32 v35, v29, v35, v29
	v_mul_f32_e32 v34, 0x3f4c422a, v34
	v_mul_f32_e32 v35, 0x3f4c422a, v35
	v_add_f32_e32 v34, v34, v34
	v_add_f32_e32 v35, v35, v35
	v_mul_f32_e32 v34, 0x3fb8aa3b, v34
	v_mul_f32_e32 v35, 0x3fb8aa3b, v35
	v_exp_f32_e32 v34, v34
	v_exp_f32_e32 v35, v35
	v_mul_f32_e32 v24, 0xbfb8aa3b, v24
	v_mul_f32_e32 v25, 0xbfb8aa3b, v25
	v_exp_f32_e32 v24, v24
	v_pk_add_f32 v[34:35], v[34:35], 1.0 op_sel_hi:[1,0]
	v_exp_f32_e32 v25, v25
	s_nop 0
	v_pk_add_f32 v[24:25], v[24:25], 1.0 op_sel_hi:[1,0]
	v_pk_mul_f32 v[28:29], v[28:29], 0.5 op_sel_hi:[1,0]
	v_mul_f32_e32 v27, 0xbfb8aa3b, v27
	v_rcp_f32_e32 v35, v35
	s_nop 0
	v_mul_f32_e32 v35, 2.0, v35
	v_exp_f32_e32 v27, v27
	v_rcp_f32_e32 v34, v34
	s_nop 0
	v_mul_f32_e32 v34, 2.0, v34
	v_pk_add_f32 v[34:35], v[34:35], 1.0 op_sel_hi:[1,0] neg_lo:[1,0] neg_hi:[1,0]
	v_mul_f32_e32 v16, 0xbfb8aa3b, v16
	v_pk_add_f32 v[34:35], v[34:35], 1.0 op_sel_hi:[1,0]
	v_mul_f32_e32 v17, 0xbfb8aa3b, v17
	v_pk_mul_f32 v[28:29], v[28:29], v[34:35]
	v_rcp_f32_e32 v25, v25
	v_exp_f32_e32 v16, v16
	v_rcp_f32_e32 v24, v24
	s_nop 0
	v_pk_mul_f32 v[24:25], v[28:29], v[24:25]
	v_mul_f32_e32 v28, 0x3d372713, v30
	v_mul_f32_e32 v29, 0x3d372713, v31
	v_mul_f32_e32 v28, v30, v28
	v_mul_f32_e32 v29, v31, v29
	v_fma_f32 v28, v30, v28, v30
	v_fma_f32 v29, v31, v29, v31
	v_mul_f32_e32 v28, 0x3f4c422a, v28
	v_mul_f32_e32 v29, 0x3f4c422a, v29
	v_add_f32_e32 v28, v28, v28
	v_add_f32_e32 v29, v29, v29
	v_mul_f32_e32 v28, 0x3fb8aa3b, v28
	v_mul_f32_e32 v29, 0x3fb8aa3b, v29
	v_exp_f32_e32 v28, v28
	v_exp_f32_e32 v29, v29
	v_cvt_pk_bf16_f32 v24, v24, v25
	v_mul_f32_e32 v25, 0xbfb8aa3b, v26
	v_exp_f32_e32 v26, v25
	v_pk_add_f32 v[28:29], v[28:29], 1.0 op_sel_hi:[1,0]
	v_pk_mul_f32 v[30:31], v[30:31], 0.5 op_sel_hi:[1,0]
	v_pk_add_f32 v[26:27], v[26:27], 1.0 op_sel_hi:[1,0]
	v_exp_f32_e32 v17, v17
	v_ashrrev_i32_e32 v33, 31, v32
	v_rcp_f32_e32 v29, v29
	s_nop 0
	v_mul_f32_e32 v29, 2.0, v29
	v_pk_add_f32 v[16:17], v[16:17], 1.0 op_sel_hi:[1,0]
	v_rcp_f32_e32 v28, v28
	s_nop 0
	v_mul_f32_e32 v28, 2.0, v28
	v_pk_add_f32 v[28:29], v[28:29], 1.0 op_sel_hi:[1,0] neg_lo:[1,0] neg_hi:[1,0]
	v_lshlrev_b64 v[32:33], 11, v[32:33]
	v_pk_add_f32 v[28:29], v[28:29], 1.0 op_sel_hi:[1,0]
	s_nop 0
	v_pk_mul_f32 v[28:29], v[30:31], v[28:29]
	v_rcp_f32_e32 v27, v27
	v_rcp_f32_e32 v26, v26
	v_mul_f32_e32 v25, 0x3d372713, v20
	v_mul_f32_e32 v25, v20, v25
	v_fma_f32 v25, v20, v25, v20
	v_mul_f32_e32 v25, 0x3f4c422a, v25
	v_add_f32_e32 v25, v25, v25
	v_mul_f32_e32 v25, 0x3fb8aa3b, v25
	v_pk_mul_f32 v[26:27], v[28:29], v[26:27]
	v_exp_f32_e32 v28, v25
	v_mul_f32_e32 v25, 0x3d372713, v21
	v_mul_f32_e32 v25, v21, v25
	v_fma_f32 v25, v21, v25, v21
	v_mul_f32_e32 v25, 0x3f4c422a, v25
	v_add_f32_e32 v25, v25, v25
	v_mul_f32_e32 v25, 0x3fb8aa3b, v25
	v_exp_f32_e32 v29, v25
	v_cvt_pk_bf16_f32 v25, v26, v27
	v_pk_mul_f32 v[20:21], v[20:21], 0.5 op_sel_hi:[1,0]
	v_pk_add_f32 v[26:27], v[28:29], 1.0 op_sel_hi:[1,0]
	s_nop 0
	s_nop 0
	v_rcp_f32_e32 v27, v27
	s_nop 0
	v_mul_f32_e32 v27, 2.0, v27
	v_rcp_f32_e32 v26, v26
	s_nop 0
	v_mul_f32_e32 v26, 2.0, v26
	v_pk_add_f32 v[26:27], v[26:27], 1.0 op_sel_hi:[1,0] neg_lo:[1,0] neg_hi:[1,0]
	s_nop 0
	v_pk_add_f32 v[26:27], v[26:27], 1.0 op_sel_hi:[1,0]
	s_nop 0
	v_pk_mul_f32 v[20:21], v[20:21], v[26:27]
	v_rcp_f32_e32 v17, v17
	v_rcp_f32_e32 v16, v16
	s_nop 0
	v_pk_mul_f32 v[16:17], v[20:21], v[16:17]
	v_mul_f32_e32 v20, 0x3d372713, v22
	v_mul_f32_e32 v21, 0x3d372713, v23
	v_mul_f32_e32 v20, v22, v20
	v_mul_f32_e32 v21, v23, v21
	v_fma_f32 v20, v22, v20, v22
	v_fma_f32 v21, v23, v21, v23
	v_mul_f32_e32 v20, 0x3f4c422a, v20
	v_mul_f32_e32 v21, 0x3f4c422a, v21
	v_add_f32_e32 v20, v20, v20
	v_add_f32_e32 v21, v21, v21
	v_mul_f32_e32 v20, 0x3fb8aa3b, v20
	v_mul_f32_e32 v21, 0x3fb8aa3b, v21
	v_exp_f32_e32 v20, v20
	v_exp_f32_e32 v21, v21
	v_cvt_pk_bf16_f32 v26, v16, v17
	v_mul_f32_e32 v16, 0xbfb8aa3b, v18
	v_mul_f32_e32 v17, 0xbfb8aa3b, v19
	v_pk_add_f32 v[20:21], v[20:21], 1.0 op_sel_hi:[1,0]
	v_pk_mul_f32 v[18:19], v[22:23], 0.5 op_sel_hi:[1,0]
	v_exp_f32_e32 v16, v16
	v_exp_f32_e32 v17, v17
	v_rcp_f32_e32 v21, v21
	s_nop 0
	v_mul_f32_e32 v21, 2.0, v21
	v_pk_add_f32 v[16:17], v[16:17], 1.0 op_sel_hi:[1,0]
	v_rcp_f32_e32 v20, v20
	s_nop 0
	v_mul_f32_e32 v20, 2.0, v20
	v_pk_add_f32 v[20:21], v[20:21], 1.0 op_sel_hi:[1,0] neg_lo:[1,0] neg_hi:[1,0]
	s_nop 0
	v_pk_add_f32 v[20:21], v[20:21], 1.0 op_sel_hi:[1,0]
	s_nop 0
	v_pk_mul_f32 v[18:19], v[18:19], v[20:21]
	v_rcp_f32_e32 v17, v17
	v_rcp_f32_e32 v16, v16
	s_nop 0
	v_pk_mul_f32 v[16:17], v[18:19], v[16:17]
	s_nop 0
	v_cvt_pk_bf16_f32 v27, v16, v17
	v_lshl_add_u64 v[16:17], s[8:9], 0, v[32:33]
	v_lshl_add_u64 v[16:17], v[144:145], 1, v[16:17]
	global_store_dwordx4 v[16:17], v[24:27], off nt
; __device__ __forceinline__ unsigned cvt_pk_bf16(float lo, float hi) { const f32x2 v = {lo, hi}; return __builtin_bit_cast(unsigned, __builtin_convertvector(v, bf16x2_t)); }
; __device__ __forceinline__ float sigm(float x) { return 1.0f / (1.0f + __expf(-x)); }
; __device__ __forceinline__ float gelu_t(float x) { float u = 0.7978845608028654f * (x + 0.044715f * x * x * x); return 0.5f * x * (1.0f + tanh_(u)); }
;     __device__ __forceinline__ void operator()(AccRef acc, const Unit& u, int wr, int wc, int fr, int fq) const {
;     ...
;                     const f32x4 g0 = acc[ai][0][m][0], g1 = acc[ai][0][m][1], s0 = acc[ai][1][m][0], s1 = acc[ai][1][m][1];
;                     u32x4 w;
;                     w.x = cvt_pk_bf16(gelu_t(g0[0]) * sigm(s0[0]), gelu_t(g0[1]) * sigm(s0[1])); w.y = cvt_pk_bf16(gelu_t(g0[2]) * sigm(s0[2]), gelu_t(g0[3]) * sigm(s0[3]));
;                     w.z = cvt_pk_bf16(gelu_t(g1[0]) * sigm(s1[0]), gelu_t(g1[1]) * sigm(s1[1])); w.w = cvt_pk_bf16(gelu_t(g1[2]) * sigm(s1[2]), gelu_t(g1[3]) * sigm(s1[3]));
;                     if (EPI_ROWS(ai, m) < MT) *(u32x4*)(GG + (size_t)EPI_ROWS(ai, m) * D + col0) = w;
.LBB0_608:
	s_or_b64 exec, exec, s[2:3]
	v_add_u32_e32 v16, 0xb0, v128
	v_cmp_gt_i32_e32 vcc, s91, v16
	s_and_saveexec_b64 s[2:3], vcc
	s_cbranch_execz .LBB0_610
	v_mul_f32_e32 v18, 0x3d372713, v12
	v_mul_f32_e32 v19, 0x3d372713, v13
	v_mul_f32_e32 v18, v12, v18
	v_mul_f32_e32 v19, v13, v19
	v_fma_f32 v18, v12, v18, v12
	v_fma_f32 v19, v13, v19, v13
	v_mul_f32_e32 v18, 0x3f4c422a, v18
	v_mul_f32_e32 v19, 0x3f4c422a, v19
	v_add_f32_e32 v18, v18, v18
	v_add_f32_e32 v19, v19, v19
	v_mul_f32_e32 v18, 0x3fb8aa3b, v18
	v_mul_f32_e32 v19, 0x3fb8aa3b, v19
	v_exp_f32_e32 v18, v18
	v_exp_f32_e32 v19, v19
	v_mul_f32_e32 v8, 0xbfb8aa3b, v8
	v_mul_f32_e32 v9, 0xbfb8aa3b, v9
	v_exp_f32_e32 v8, v8
	v_pk_add_f32 v[18:19], v[18:19], 1.0 op_sel_hi:[1,0]
	v_exp_f32_e32 v9, v9
	s_nop 0
	v_pk_add_f32 v[8:9], v[8:9], 1.0 op_sel_hi:[1,0]
	v_pk_mul_f32 v[12:13], v[12:13], 0.5 op_sel_hi:[1,0]
	v_mul_f32_e32 v11, 0xbfb8aa3b, v11
	v_rcp_f32_e32 v19, v19
	s_nop 0
	v_mul_f32_e32 v19, 2.0, v19
	v_exp_f32_e32 v11, v11
	v_rcp_f32_e32 v18, v18
	s_nop 0
	v_mul_f32_e32 v18, 2.0, v18
	v_pk_add_f32 v[18:19], v[18:19], 1.0 op_sel_hi:[1,0] neg_lo:[1,0] neg_hi:[1,0]
	v_mul_f32_e32 v0, 0xbfb8aa3b, v0
	v_pk_add_f32 v[18:19], v[18:19], 1.0 op_sel_hi:[1,0]
	v_mul_f32_e32 v1, 0xbfb8aa3b, v1
	v_pk_mul_f32 v[12:13], v[12:13], v[18:19]
	v_rcp_f32_e32 v9, v9
	v_exp_f32_e32 v0, v0
	v_rcp_f32_e32 v8, v8
	s_nop 0
	v_pk_mul_f32 v[8:9], v[12:13], v[8:9]
	v_mul_f32_e32 v12, 0x3d372713, v14
	v_mul_f32_e32 v13, 0x3d372713, v15
	v_mul_f32_e32 v12, v14, v12
	v_mul_f32_e32 v13, v15, v13
	v_fma_f32 v12, v14, v12, v14
	v_fma_f32 v13, v15, v13, v15
	v_mul_f32_e32 v12, 0x3f4c422a, v12
	v_mul_f32_e32 v13, 0x3f4c422a, v13
	v_add_f32_e32 v12, v12, v12
	v_add_f32_e32 v13, v13, v13
	v_mul_f32_e32 v12, 0x3fb8aa3b, v12
	v_mul_f32_e32 v13, 0x3fb8aa3b, v13
	v_exp_f32_e32 v12, v12
	v_exp_f32_e32 v13, v13
	v_cvt_pk_bf16_f32 v8, v8, v9
	v_mul_f32_e32 v9, 0xbfb8aa3b, v10
	v_exp_f32_e32 v10, v9
	v_pk_add_f32 v[12:13], v[12:13], 1.0 op_sel_hi:[1,0]
	v_pk_mul_f32 v[14:15], v[14:15], 0.5 op_sel_hi:[1,0]
	v_pk_add_f32 v[10:11], v[10:11], 1.0 op_sel_hi:[1,0]
	v_exp_f32_e32 v1, v1
	v_ashrrev_i32_e32 v17, 31, v16
	v_rcp_f32_e32 v13, v13
	s_nop 0
	v_mul_f32_e32 v13, 2.0, v13
	v_pk_add_f32 v[0:1], v[0:1], 1.0 op_sel_hi:[1,0]
	v_rcp_f32_e32 v12, v12
	s_nop 0
	v_mul_f32_e32 v12, 2.0, v12
	v_pk_add_f32 v[12:13], v[12:13], 1.0 op_sel_hi:[1,0] neg_lo:[1,0] neg_hi:[1,0]
	v_lshlrev_b64 v[16:17], 11, v[16:17]
	v_pk_add_f32 v[12:13], v[12:13], 1.0 op_sel_hi:[1,0]
	s_nop 0
	v_pk_mul_f32 v[12:13], v[14:15], v[12:13]
	v_rcp_f32_e32 v11, v11
	v_rcp_f32_e32 v10, v10
	v_mul_f32_e32 v9, 0x3d372713, v4
	v_mul_f32_e32 v9, v4, v9
	v_fma_f32 v9, v4, v9, v4
	v_mul_f32_e32 v9, 0x3f4c422a, v9
	v_add_f32_e32 v9, v9, v9
	v_mul_f32_e32 v9, 0x3fb8aa3b, v9
	v_pk_mul_f32 v[10:11], v[12:13], v[10:11]
	v_exp_f32_e32 v12, v9
	v_mul_f32_e32 v9, 0x3d372713, v5
	v_mul_f32_e32 v9, v5, v9
	v_fma_f32 v9, v5, v9, v5
	v_mul_f32_e32 v9, 0x3f4c422a, v9
	v_add_f32_e32 v9, v9, v9
	v_mul_f32_e32 v9, 0x3fb8aa3b, v9
	v_exp_f32_e32 v13, v9
	v_cvt_pk_bf16_f32 v9, v10, v11
	v_pk_mul_f32 v[4:5], v[4:5], 0.5 op_sel_hi:[1,0]
	v_pk_add_f32 v[10:11], v[12:13], 1.0 op_sel_hi:[1,0]
	s_nop 0
	s_nop 0
	v_rcp_f32_e32 v11, v11
	s_nop 0
	v_mul_f32_e32 v11, 2.0, v11
	v_rcp_f32_e32 v10, v10
	s_nop 0
	v_mul_f32_e32 v10, 2.0, v10
	v_pk_add_f32 v[10:11], v[10:11], 1.0 op_sel_hi:[1,0] neg_lo:[1,0] neg_hi:[1,0]
	s_nop 0
	v_pk_add_f32 v[10:11], v[10:11], 1.0 op_sel_hi:[1,0]
	s_nop 0
	v_pk_mul_f32 v[4:5], v[4:5], v[10:11]
	v_rcp_f32_e32 v1, v1
	v_rcp_f32_e32 v0, v0
	s_nop 0
	v_pk_mul_f32 v[0:1], v[4:5], v[0:1]
	v_mul_f32_e32 v4, 0x3d372713, v6
	v_mul_f32_e32 v5, 0x3d372713, v7
	v_mul_f32_e32 v4, v6, v4
	v_mul_f32_e32 v5, v7, v5
	v_fma_f32 v4, v6, v4, v6
	v_fma_f32 v5, v7, v5, v7
	v_mul_f32_e32 v4, 0x3f4c422a, v4
	v_mul_f32_e32 v5, 0x3f4c422a, v5
	v_add_f32_e32 v4, v4, v4
	v_add_f32_e32 v5, v5, v5
	v_mul_f32_e32 v4, 0x3fb8aa3b, v4
	v_mul_f32_e32 v5, 0x3fb8aa3b, v5
	v_exp_f32_e32 v4, v4
	v_exp_f32_e32 v5, v5
	v_cvt_pk_bf16_f32 v10, v0, v1
	v_mul_f32_e32 v0, 0xbfb8aa3b, v2
	v_mul_f32_e32 v1, 0xbfb8aa3b, v3
	v_pk_add_f32 v[4:5], v[4:5], 1.0 op_sel_hi:[1,0]
	v_pk_mul_f32 v[2:3], v[6:7], 0.5 op_sel_hi:[1,0]
	v_exp_f32_e32 v0, v0
	v_exp_f32_e32 v1, v1
	v_rcp_f32_e32 v5, v5
	s_nop 0
	v_mul_f32_e32 v5, 2.0, v5
	v_pk_add_f32 v[0:1], v[0:1], 1.0 op_sel_hi:[1,0]
	v_rcp_f32_e32 v4, v4
	s_nop 0
	v_mul_f32_e32 v4, 2.0, v4
	v_pk_add_f32 v[4:5], v[4:5], 1.0 op_sel_hi:[1,0] neg_lo:[1,0] neg_hi:[1,0]
	s_nop 0
	v_pk_add_f32 v[4:5], v[4:5], 1.0 op_sel_hi:[1,0]
	s_nop 0
	v_pk_mul_f32 v[2:3], v[2:3], v[4:5]
	v_rcp_f32_e32 v1, v1
	v_rcp_f32_e32 v0, v0
	s_nop 0
	v_pk_mul_f32 v[0:1], v[2:3], v[0:1]
	s_nop 0
	v_cvt_pk_bf16_f32 v11, v0, v1
	v_lshl_add_u64 v[0:1], s[8:9], 0, v[16:17]
	v_lshl_add_u64 v[0:1], v[144:145], 1, v[0:1]
	global_store_dwordx4 v[0:1], v[8:11], off nt

; #define LAS __attribute__((address_space(3)))
; __device__ __forceinline__ unsigned cvt_pk_bf16(float lo, float hi) { const f32x2 v = {lo, hi}; return __builtin_bit_cast(unsigned, __builtin_convertvector(v, bf16x2_t)); }
; __device__ __forceinline__ void transpose_item(const float* W, int K, int N, bf16_t* WT, int mapmode, LAS float* scr, int item, int lane) {
;     ...
;     const int c = lane & 7, d0 = map_row(mapmode, n0);
; #pragma unroll
;     for (int j = 0; j < 4; ++j) { const int n = (lane >> 3) + 8 * j; const LAS float* s = scr + (8 * c) * 33 + n;
;         u32x4 o; o.x = cvt_pk_bf16(s[0 * 33], s[1 * 33]); o.y = cvt_pk_bf16(s[2 * 33], s[3 * 33]); o.z = cvt_pk_bf16(s[4 * 33], s[5 * 33]); o.w = cvt_pk_bf16(s[6 * 33], s[7 * 33]);
;         *(u32x4*)(WT + (size_t)(d0 + n) * K + k0 + 8 * c) = o; }
.LBB0_616:
	ds_read2_b32 v[28:29], v12 offset0:33 offset1:41
	ds_read2_b32 v[30:31], v12 offset1:8
	ds_read2_b32 v[32:33], v12 offset0:66 offset1:74
	ds_read2_b32 v[34:35], v12 offset0:99 offset1:107
	ds_read2_b32 v[36:37], v12 offset0:132 offset1:140
	ds_read2_b32 v[38:39], v12 offset0:165 offset1:173
	ds_read2_b32 v[40:41], v12 offset0:198 offset1:206
	ds_read2_b32 v[42:43], v12 offset0:231 offset1:239
	v_add_u32_e32 v46, s5, v11
	s_ashr_i32 s3, s2, 31
	v_ashrrev_i32_e32 v47, 31, v46
	v_lshl_add_u64 v[44:45], s[2:3], 1, v[4:5]
	v_lshlrev_b64 v[46:47], 11, v[46:47]
	s_waitcnt lgkmcnt(6)
	v_cvt_pk_bf16_f32 v24, v30, v28
	s_waitcnt lgkmcnt(4)
	v_cvt_pk_bf16_f32 v25, v32, v34
	s_waitcnt lgkmcnt(2)
	v_cvt_pk_bf16_f32 v26, v36, v38
	s_waitcnt lgkmcnt(0)
	v_cvt_pk_bf16_f32 v27, v40, v42
	v_lshl_add_u64 v[46:47], v[44:45], 0, v[46:47]
	v_add_u32_e32 v28, s5, v13
	global_store_dwordx4 v[46:47], v[24:27], off nt
	s_nop 1
	v_cvt_pk_bf16_f32 v24, v31, v29
	v_ashrrev_i32_e32 v29, 31, v28
	v_cvt_pk_bf16_f32 v25, v33, v35
	v_cvt_pk_bf16_f32 v26, v37, v39
	v_cvt_pk_bf16_f32 v27, v41, v43
	v_lshlrev_b64 v[28:29], 11, v[28:29]
	ds_read2_b32 v[30:31], v12 offset0:49 offset1:57
	ds_read2_b32 v[32:33], v12 offset0:16 offset1:24
	ds_read2_b32 v[34:35], v12 offset0:82 offset1:90
	ds_read2_b32 v[36:37], v12 offset0:115 offset1:123
	ds_read2_b32 v[38:39], v12 offset0:148 offset1:156
	ds_read2_b32 v[40:41], v12 offset0:181 offset1:189
	ds_read2_b32 v[42:43], v12 offset0:214 offset1:222
	ds_read2_b32 v[46:47], v12 offset0:247 offset1:255
	v_lshl_add_u64 v[28:29], v[44:45], 0, v[28:29]
	global_store_dwordx4 v[28:29], v[24:27], off nt
	v_add_u32_e32 v28, s5, v14
	v_ashrrev_i32_e32 v29, 31, v28
	v_lshlrev_b64 v[28:29], 11, v[28:29]
	s_waitcnt lgkmcnt(6)
	v_cvt_pk_bf16_f32 v24, v32, v30
	s_waitcnt lgkmcnt(4)
	v_cvt_pk_bf16_f32 v25, v34, v36
	s_waitcnt lgkmcnt(2)
	v_cvt_pk_bf16_f32 v26, v38, v40
	s_waitcnt lgkmcnt(0)
	v_cvt_pk_bf16_f32 v27, v42, v46
	v_lshl_add_u64 v[28:29], v[44:45], 0, v[28:29]
	global_store_dwordx4 v[28:29], v[24:27], off nt
	v_add_u32_e32 v28, s5, v15
	v_ashrrev_i32_e32 v29, 31, v28
	v_lshlrev_b64 v[28:29], 11, v[28:29]
	v_cvt_pk_bf16_f32 v24, v33, v31
	v_cvt_pk_bf16_f32 v25, v35, v37
	v_cvt_pk_bf16_f32 v26, v39, v41
	v_cvt_pk_bf16_f32 v27, v43, v47
	v_lshl_add_u64 v[28:29], v[44:45], 0, v[28:29]
	global_store_dwordx4 v[28:29], v[24:27], off nt
	s_waitcnt lgkmcnt(0)

; __device__ __forceinline__ void transpose_item(const float* W, int K, int N, bf16_t* WT, int mapmode, LAS float* scr, int item, int lane) {
;     const int nblk = N / 32, kb = item / nblk, nb = item % nblk, k0 = 64 * kb, n0 = 32 * nb;
;     float tv[32];
; #pragma unroll
;     for (int i = 0; i < 32; ++i) tv[i] = W[(size_t)(k0 + 2 * i + (lane >> 5)) * N + n0 + (lane & 31)];
; template <int ph>
; __device__ __forceinline__ void run_phase(const Args& args, LAS unsigned char* lds, const int G, const int bx, const bool fin = true) {
;     ...
;             for (int it = gw2; it < I_WI + I_WO; it += ngw2) { if (it < I_WI) transpose_item(INP(13), D, 2 * FF, WI, 1, scr, it, lane); else transpose_item(INP(14), FF, D, WO, 0, scr, it - I_WI, lane); } } }
.LBB0_618:
	s_cmpk_gt_i32 s8, 0xaff
	s_mov_b64 s[2:3], -1
	s_cbranch_scc0 .LBB0_620
	s_and_b32 s3, s15, 0x1ffc0
	s_and_b32 s2, s10, 0x3e0
	v_or_b32_e32 v0, s3, v10
	s_lshl_b32 s0, s2, 2
	v_lshl_add_u64 v[24:25], v[6:7], 0, s[0:1]
	v_lshlrev_b32_e32 v0, 12, v0
	v_lshl_add_u64 v[24:25], v[24:25], 0, v[0:1]
	v_add_co_u32_e32 v26, vcc, 0x2000, v24
	s_lshl_b32 s0, s3, 1
	s_nop 0
	v_addc_co_u32_e32 v27, vcc, 0, v25, vcc
	v_add_co_u32_e32 v28, vcc, 0x4000, v24
	s_nop 1
	v_addc_co_u32_e32 v29, vcc, 0, v25, vcc
	v_add_co_u32_e32 v30, vcc, 0x6000, v24
	s_nop 1
	v_addc_co_u32_e32 v31, vcc, 0, v25, vcc
	v_add_co_u32_e32 v32, vcc, 0x8000, v24
	s_nop 1
	v_addc_co_u32_e32 v33, vcc, 0, v25, vcc
	v_add_co_u32_e32 v34, vcc, 0xa000, v24
	s_nop 1
	v_addc_co_u32_e32 v35, vcc, 0, v25, vcc
	v_add_co_u32_e32 v36, vcc, 0xc000, v24
	s_nop 1
	v_addc_co_u32_e32 v37, vcc, 0, v25, vcc
	v_add_co_u32_e32 v38, vcc, 0xe000, v24
	s_nop 1
	v_addc_co_u32_e32 v39, vcc, 0, v25, vcc
	global_load_dword v0, v[24:25], off
	global_load_dword v42, v[26:27], off
	global_load_dword v43, v[28:29], off
	global_load_dword v44, v[30:31], off
	global_load_dword v45, v[32:33], off
	global_load_dword v46, v[34:35], off
	global_load_dword v47, v[36:37], off
	global_load_dword v48, v[38:39], off
	v_add_co_u32_e32 v26, vcc, 0x10000, v24
	s_nop 1
	v_addc_co_u32_e32 v27, vcc, 0, v25, vcc
	v_add_co_u32_e32 v28, vcc, 0x12000, v24
	s_nop 1
	v_addc_co_u32_e32 v29, vcc, 0, v25, vcc
	v_add_co_u32_e32 v30, vcc, 0x14000, v24
	s_nop 1
	v_addc_co_u32_e32 v31, vcc, 0, v25, vcc
	v_add_co_u32_e32 v32, vcc, 0x16000, v24
	s_nop 1
	v_addc_co_u32_e32 v33, vcc, 0, v25, vcc
	v_add_co_u32_e32 v34, vcc, 0x18000, v24
	s_nop 1
	v_addc_co_u32_e32 v35, vcc, 0, v25, vcc
	v_add_co_u32_e32 v36, vcc, 0x1a000, v24
	s_nop 1
	v_addc_co_u32_e32 v37, vcc, 0, v25, vcc
	v_add_co_u32_e32 v38, vcc, 0x1c000, v24
	s_nop 1
	v_addc_co_u32_e32 v39, vcc, 0, v25, vcc
	v_add_co_u32_e32 v40, vcc, 0x1e000, v24
	s_nop 1
	v_addc_co_u32_e32 v41, vcc, 0, v25, vcc
	global_load_dword v49, v[26:27], off
	global_load_dword v50, v[28:29], off
	global_load_dword v51, v[30:31], off
	global_load_dword v52, v[32:33], off
	global_load_dword v53, v[34:35], off
	global_load_dword v54, v[36:37], off
	global_load_dword v55, v[38:39], off
	global_load_dword v56, v[40:41], off
	v_add_co_u32_e32 v26, vcc, 0x20000, v24
	s_nop 1
	v_addc_co_u32_e32 v27, vcc, 0, v25, vcc
	v_add_co_u32_e32 v28, vcc, 0x22000, v24
	s_nop 1
	v_addc_co_u32_e32 v29, vcc, 0, v25, vcc
	v_add_co_u32_e32 v30, vcc, 0x24000, v24
	s_nop 1
	v_addc_co_u32_e32 v31, vcc, 0, v25, vcc
	v_add_co_u32_e32 v32, vcc, 0x26000, v24
	s_nop 1
	v_addc_co_u32_e32 v33, vcc, 0, v25, vcc
	v_add_co_u32_e32 v34, vcc, 0x28000, v24
	s_nop 1
	v_addc_co_u32_e32 v35, vcc, 0, v25, vcc
	v_add_co_u32_e32 v36, vcc, 0x2a000, v24
	s_nop 1
	v_addc_co_u32_e32 v37, vcc, 0, v25, vcc
	v_add_co_u32_e32 v38, vcc, 0x2c000, v24
	s_nop 1
	v_addc_co_u32_e32 v39, vcc, 0, v25, vcc
	v_add_co_u32_e32 v40, vcc, 0x2e000, v24
	s_nop 1
	v_addc_co_u32_e32 v41, vcc, 0, v25, vcc
	global_load_dword v57, v[26:27], off
	global_load_dword v58, v[28:29], off
	global_load_dword v59, v[30:31], off
	global_load_dword v60, v[32:33], off
	global_load_dword v61, v[34:35], off
	global_load_dword v62, v[36:37], off
	global_load_dword v63, v[38:39], off
	s_nop 0
	global_load_dword v40, v[40:41], off
	v_add_co_u32_e32 v26, vcc, 0x30000, v24
	s_nop 1
	v_addc_co_u32_e32 v27, vcc, 0, v25, vcc
	v_add_co_u32_e32 v28, vcc, 0x32000, v24
	s_nop 1
	v_addc_co_u32_e32 v29, vcc, 0, v25, vcc
	v_add_co_u32_e32 v30, vcc, 0x34000, v24
	s_nop 1
	v_addc_co_u32_e32 v31, vcc, 0, v25, vcc
	v_add_co_u32_e32 v32, vcc, 0x36000, v24
	s_nop 1
	v_addc_co_u32_e32 v33, vcc, 0, v25, vcc
	v_add_co_u32_e32 v34, vcc, 0x38000, v24
	s_nop 1
	v_addc_co_u32_e32 v35, vcc, 0, v25, vcc
	v_add_co_u32_e32 v36, vcc, 0x3a000, v24
	s_nop 1
	v_addc_co_u32_e32 v37, vcc, 0, v25, vcc
	v_add_co_u32_e32 v38, vcc, 0x3c000, v24
	s_nop 1
	v_addc_co_u32_e32 v39, vcc, 0, v25, vcc
	v_add_co_u32_e32 v24, vcc, 0x3e000, v24
	s_nop 1
	v_addc_co_u32_e32 v25, vcc, 0, v25, vcc
	global_load_dword v26, v[26:27], off
	s_nop 0
	global_load_dword v27, v[28:29], off
	s_nop 0
	global_load_dword v28, v[30:31], off
	global_load_dword v29, v[32:33], off
	s_nop 0
	global_load_dword v30, v[34:35], off
	global_load_dword v31, v[36:37], off
	global_load_dword v32, v[38:39], off
	s_nop 0
	global_load_dword v24, v[24:25], off
	s_waitcnt vmcnt(0)
; #define LAS __attribute__((address_space(3)))
; __device__ __forceinline__ unsigned cvt_pk_bf16(float lo, float hi) { const f32x2 v = {lo, hi}; return __builtin_bit_cast(unsigned, __builtin_convertvector(v, bf16x2_t)); }
; __device__ __forceinline__ void transpose_item(const float* W, int K, int N, bf16_t* WT, int mapmode, LAS float* scr, int item, int lane) {
;     ...
;     for (int i = 0; i < 32; ++i) scr[(2 * i + (lane >> 5)) * 33 + (lane & 31)] = tv[i];
;     asm volatile("s_waitcnt lgkmcnt(0)" ::: "memory");
;     const int c = lane & 7, d0 = map_row(mapmode, n0);
; #pragma unroll
;     for (int j = 0; j < 4; ++j) { const int n = (lane >> 3) + 8 * j; const LAS float* s = scr + (8 * c) * 33 + n;
;         u32x4 o; o.x = cvt_pk_bf16(s[0 * 33], s[1 * 33]); o.y = cvt_pk_bf16(s[2 * 33], s[3 * 33]); o.z = cvt_pk_bf16(s[4 * 33], s[5 * 33]); o.w = cvt_pk_bf16(s[6 * 33], s[7 * 33]);
;         *(u32x4*)(WT + (size_t)(d0 + n) * K + k0 + 8 * c) = o; }
	ds_write2_b32 v16, v0, v42 offset1:66
	ds_write2_b32 v16, v43, v44 offset0:132 offset1:198
	ds_write2_b32 v17, v45, v46 offset0:8 offset1:74
	ds_write2_b32 v17, v47, v48 offset0:140 offset1:206
	ds_write2_b32 v18, v49, v50 offset0:16 offset1:82
	ds_write2_b32 v18, v51, v52 offset0:148 offset1:214
	ds_write2_b32 v19, v53, v54 offset0:24 offset1:90
	ds_write2_b32 v19, v55, v56 offset0:156 offset1:222
	ds_write2_b32 v20, v57, v58 offset0:32 offset1:98
	ds_write2_b32 v20, v59, v60 offset0:164 offset1:230
	ds_write2_b32 v21, v61, v62 offset0:40 offset1:106
	ds_write2_b32 v21, v63, v40 offset0:172 offset1:238
	ds_write2_b32 v22, v26, v27 offset0:48 offset1:114
	ds_write2_b32 v22, v28, v29 offset0:180 offset1:246
	ds_write2_b32 v23, v30, v31 offset0:56 offset1:122
	ds_write2_b32 v23, v32, v24 offset0:188 offset1:254
	s_waitcnt lgkmcnt(0)
	ds_read2_b32 v[28:29], v12 offset0:33 offset1:41
	ds_read2_b32 v[30:31], v12 offset1:8
	ds_read2_b32 v[32:33], v12 offset0:66 offset1:74
	ds_read2_b32 v[34:35], v12 offset0:99 offset1:107
	ds_read2_b32 v[36:37], v12 offset0:132 offset1:140
	ds_read2_b32 v[38:39], v12 offset0:165 offset1:173
	ds_read2_b32 v[40:41], v12 offset0:198 offset1:206
	ds_read2_b32 v[42:43], v12 offset0:231 offset1:239
	v_or_b32_e32 v0, s2, v11
	v_mul_u32_u24_e32 v0, 0xb00, v0
	v_lshl_add_u64 v[44:45], v[2:3], 0, s[0:1]
	v_lshlrev_b32_e32 v0, 1, v0
	v_lshl_add_u64 v[46:47], v[44:45], 0, v[0:1]
	v_or_b32_e32 v0, s2, v13
	s_waitcnt lgkmcnt(6)
	v_cvt_pk_bf16_f32 v24, v30, v28
	s_waitcnt lgkmcnt(4)
	v_cvt_pk_bf16_f32 v25, v32, v34
	s_waitcnt lgkmcnt(2)
	v_cvt_pk_bf16_f32 v26, v36, v38
	s_waitcnt lgkmcnt(0)
	v_cvt_pk_bf16_f32 v27, v40, v42
	v_mul_u32_u24_e32 v0, 0xb00, v0
	global_store_dwordx4 v[46:47], v[24:27], off nt
	v_lshlrev_b32_e32 v0, 1, v0
	s_nop 0
	v_cvt_pk_bf16_f32 v24, v31, v29
	v_cvt_pk_bf16_f32 v25, v33, v35
	v_cvt_pk_bf16_f32 v26, v37, v39
	v_cvt_pk_bf16_f32 v27, v41, v43
	v_lshl_add_u64 v[28:29], v[44:45], 0, v[0:1]
	ds_read2_b32 v[30:31], v12 offset0:16 offset1:24
	ds_read2_b32 v[32:33], v12 offset0:49 offset1:57
	ds_read2_b32 v[34:35], v12 offset0:82 offset1:90
	ds_read2_b32 v[36:37], v12 offset0:115 offset1:123
	ds_read2_b32 v[38:39], v12 offset0:148 offset1:156
	ds_read2_b32 v[40:41], v12 offset0:181 offset1:189
	ds_read2_b32 v[42:43], v12 offset0:214 offset1:222
	ds_read2_b32 v[46:47], v12 offset0:247 offset1:255
	v_or_b32_e32 v0, s2, v14
	v_mul_u32_u24_e32 v0, 0xb00, v0
	v_lshlrev_b32_e32 v0, 1, v0
	global_store_dwordx4 v[28:29], v[24:27], off nt
	v_lshl_add_u64 v[28:29], v[44:45], 0, v[0:1]
	v_or_b32_e32 v0, s2, v15
	v_mul_u32_u24_e32 v0, 0xb00, v0
	s_waitcnt lgkmcnt(6)
	v_cvt_pk_bf16_f32 v24, v30, v32
	s_waitcnt lgkmcnt(4)
	v_cvt_pk_bf16_f32 v25, v34, v36
	s_waitcnt lgkmcnt(2)
	v_cvt_pk_bf16_f32 v26, v38, v40
	s_waitcnt lgkmcnt(0)
	v_cvt_pk_bf16_f32 v27, v42, v46
	v_lshlrev_b32_e32 v0, 1, v0
	global_store_dwordx4 v[28:29], v[24:27], off nt
	v_lshl_add_u64 v[28:29], v[44:45], 0, v[0:1]
	s_mov_b64 s[2:3], 0
	v_cvt_pk_bf16_f32 v24, v31, v33
	v_cvt_pk_bf16_f32 v25, v35, v37
	v_cvt_pk_bf16_f32 v26, v39, v41
	v_cvt_pk_bf16_f32 v27, v43, v47
	global_store_dwordx4 v[28:29], v[24:27], off nt
	s_waitcnt lgkmcnt(0)
